# v48 + seam: peeled iteration's first two DMA waits relaxed to vmcnt(24) (do not wait for the epilogue stores); phase prologue drains its staging loads
# baseline (speedup 1.0000x reference)
.LBB0_244:
	v_lshlrev_b32_e32 v16, 6, v192
	v_and_b32_e32 v17, 48, v194
	s_movk_i32 s4, 0x3c0
	v_and_or_b32 v16, v16, s4, v17
	v_and_b32_e32 v1, 0xfffffc00, v1
	v_readlane_b32 s4, v254, 39
	v_lshl_add_u64 v[8:9], v[8:9], 0, s[94:95]
	s_add_i32 m0, s85, 0x18000
	v_add_u32_e32 v18, s4, v1
	v_readlane_b32 s4, v254, 43
	s_waitcnt vmcnt(2)
	s_barrier
	global_load_lds_dwordx4 v[8:9], off
	v_lshl_add_u64 v[4:5], v[4:5], 0, s[94:95]
	s_add_i32 m0, s85, 0x1a000
	s_add_i32 s43, s85, 0x8000
	s_add_i32 s90, s85, 0xa000
	v_add_u32_e32 v1, s4, v1
	global_load_lds_dwordx4 v[4:5], off
	v_lshl_add_u64 v[2:3], v[2:3], 0, s[94:95]
	s_mov_b32 m0, s43
	s_add_u32 s4, s10, 0x100080
	global_load_lds_dwordx4 v[2:3], off
	v_lshl_add_u64 v[2:3], v[6:7], 0, s[94:95]
	s_mov_b32 m0, s90
	s_addc_u32 s5, s11, 0
	global_load_lds_dwordx4 v[2:3], off
	v_lshl_add_u64 v[2:3], s[4:5], 0, v[156:157]
	s_add_i32 m0, s85, 0x1c000
	v_readlane_b32 s8, v254, 63
	global_load_lds_dwordx4 v[2:3], off
	v_lshl_add_u64 v[2:3], s[4:5], 0, v[160:161]
	s_add_i32 m0, s85, 0x1e000
	v_readlane_b32 s9, v255, 0
	global_load_lds_dwordx4 v[2:3], off
	v_add_u32_e32 v2, s97, v194
	v_ashrrev_i32_e32 v3, 31, v2
	v_lshl_add_u64 v[162:163], v[2:3], 4, s[8:9]
	v_lshlrev_b32_e32 v2, 16, v10
	v_and_b32_e32 v2, 0xfffe0000, v2
	v_lshl_add_u32 v2, v11, 13, v2
	v_and_b32_e32 v3, 1, v10
	v_lshl_or_b32 v2, v3, 6, v2
	v_lshlrev_b32_e32 v19, 2, v192
	v_lshl_add_u32 v164, v12, 1, v2
	v_lshlrev_b32_e32 v2, 16, v13
	v_and_b32_e32 v19, 32, v19
	v_and_b32_e32 v2, 0xfffe0000, v2
	v_bitop3_b32 v16, v16, v18, v19 bitop3:0xde
	v_lshlrev_b32_e32 v18, 2, v193
	s_waitcnt vmcnt(0)
	v_lshl_add_u32 v2, v14, 13, v2
	v_and_b32_e32 v3, 1, v13
	v_lshl_or_b32 v17, v193, 6, v17
	v_and_b32_e32 v18, 32, v18
	v_lshl_or_b32 v2, v3, 6, v2
	v_bitop3_b32 v1, v17, v1, v18 bitop3:0xde
	v_add_u32_e32 v147, s61, v152
	v_ashrrev_i32_e32 v153, 31, v152
	v_cmp_gt_u32_e64 s[4:5], 16, v194
	v_lshlrev_b32_e32 v195, 5, v192
	s_mov_b32 s40, 0
	v_cmp_eq_u32_e64 s[6:7], 0, v194
	v_mov_b32_e32 v165, v0
	v_lshl_add_u32 v166, v15, 1, v2
	v_mov_b32_e32 v167, v0
	v_add_u32_e32 v197, 0, v16
	s_barrier
	s_branch .LBB0_247

.LBB0_261:
	s_ashr_i32 s35, s34, 31
	s_lshl_b64 vcc, s[34:35], 21
	s_add_u32 s13, s30, vcc_lo
	s_addc_u32 s15, s31, vcc_hi
	s_add_u32 s54, s13, s54
	s_addc_u32 s55, s15, s55
	s_and_b64 s[86:87], s[86:87], exec
	s_cselect_b32 s13, s55, s11
	s_cselect_b32 s15, s54, s10
	s_add_i32 s35, s19, -2
	s_add_u32 s40, s10, 0x100
	s_addc_u32 s49, s11, 0
	s_add_u32 s10, s38, 0x100080
	s_addc_u32 s11, s39, 0
	s_mov_b32 s38, 0
	s_add_i32 vcc_lo, s38, 2
	s_add_u32 s39, s10, 0xfff00080
	s_addc_u32 s66, s11, -1
	s_add_i32 s67, 0, 0x10000
	s_cmp_eq_u32 s35, s38
	s_cselect_b32 s87, s53, s66
	s_cselect_b32 s86, s52, s39
	s_cselect_b32 s39, s13, s49
	s_cselect_b32 s38, s15, s40
	s_add_i32 vcc_hi, 0, 0x14000
	v_add_u32_e32 v142, s67, v1
	v_add_u32_e32 v180, vcc_hi, v1
	ds_read_b128 v[130:133], v142
	ds_read_b128 v[134:137], v142 offset:1024
	ds_read_b128 v[138:141], v142 offset:2048
	ds_read_b128 v[142:145], v142 offset:3072
	ds_read_b128 v[168:171], v180
	ds_read_b128 v[172:175], v180 offset:1024
	ds_read_b128 v[176:179], v180 offset:2048
	ds_read_b128 v[180:183], v180 offset:3072
	s_add_i32 m0, s85, 0xc000
	ds_read_b128 v[198:201], v197
	ds_read_b128 v[202:205], v197 offset:1024
	ds_read_b128 v[206:209], v197 offset:2048
	ds_read_b128 v[210:213], v197 offset:3072
	ds_read_b128 v[214:217], v197 offset:4096
	ds_read_b128 v[218:221], v197 offset:5120
	ds_read_b128 v[222:225], v197 offset:6144
	ds_read_b128 v[226:229], v197 offset:7168
	global_load_lds_dwordx4 v164, s[10:11]
	s_add_i32 m0, s85, 0xe000
	s_nop 0
	global_load_lds_dwordx4 v166, s[10:11]
	s_waitcnt vmcnt(24)
	s_waitcnt lgkmcnt(0)
	s_setprio 1
	s_barrier
	v_mfma_f32_16x16x32_bf16 v[114:117], v[130:133], v[198:201], 0
	v_mfma_f32_16x16x32_bf16 v[118:121], v[138:141], v[198:201], 0
	v_mfma_f32_16x16x32_bf16 v[102:105], v[130:133], v[206:209], 0
	v_mfma_f32_16x16x32_bf16 v[98:101], v[138:141], v[206:209], 0
	v_mfma_f32_16x16x32_bf16 v[86:89], v[130:133], v[214:217], 0
	v_mfma_f32_16x16x32_bf16 v[82:85], v[138:141], v[214:217], 0
	v_mfma_f32_16x16x32_bf16 v[54:57], v[130:133], v[222:225], 0
	v_mfma_f32_16x16x32_bf16 v[50:53], v[138:141], v[222:225], 0
	v_mfma_f32_16x16x32_bf16 v[114:117], v[134:137], v[202:205], v[114:117]
	v_mfma_f32_16x16x32_bf16 v[118:121], v[142:145], v[202:205], v[118:121]
	v_mfma_f32_16x16x32_bf16 v[102:105], v[134:137], v[210:213], v[102:105]
	v_mfma_f32_16x16x32_bf16 v[98:101], v[142:145], v[210:213], v[98:101]
	v_mfma_f32_16x16x32_bf16 v[86:89], v[134:137], v[218:221], v[86:89]
	v_mfma_f32_16x16x32_bf16 v[82:85], v[142:145], v[218:221], v[82:85]
	v_mfma_f32_16x16x32_bf16 v[54:57], v[134:137], v[226:229], v[54:57]
	v_mfma_f32_16x16x32_bf16 v[50:53], v[142:145], v[226:229], v[50:53]
	s_setprio 0
	s_setprio 1
	v_mfma_f32_16x16x32_bf16 v[126:129], v[168:171], v[198:201], 0
	v_mfma_f32_16x16x32_bf16 v[122:125], v[176:179], v[198:201], 0
	v_mfma_f32_16x16x32_bf16 v[110:113], v[168:171], v[206:209], 0
	v_mfma_f32_16x16x32_bf16 v[106:109], v[176:179], v[206:209], 0
	v_mfma_f32_16x16x32_bf16 v[94:97], v[168:171], v[214:217], 0
	v_mfma_f32_16x16x32_bf16 v[90:93], v[176:179], v[214:217], 0
	v_mfma_f32_16x16x32_bf16 v[70:73], v[168:171], v[222:225], 0
	v_mfma_f32_16x16x32_bf16 v[66:69], v[176:179], v[222:225], 0
	v_mfma_f32_16x16x32_bf16 v[126:129], v[172:175], v[202:205], v[126:129]
	v_mfma_f32_16x16x32_bf16 v[122:125], v[180:183], v[202:205], v[122:125]
	v_mfma_f32_16x16x32_bf16 v[110:113], v[172:175], v[210:213], v[110:113]
	v_mfma_f32_16x16x32_bf16 v[106:109], v[180:183], v[210:213], v[106:109]
	v_mfma_f32_16x16x32_bf16 v[94:97], v[172:175], v[218:221], v[94:97]
	v_mfma_f32_16x16x32_bf16 v[90:93], v[180:183], v[218:221], v[90:93]
	v_mfma_f32_16x16x32_bf16 v[70:73], v[172:175], v[226:229], v[70:73]
	v_mfma_f32_16x16x32_bf16 v[66:69], v[180:183], v[226:229], v[66:69]
	s_barrier
	s_setprio 0
	s_add_i32 s66, s67, s97
	s_add_u32 s98, s38, 0x80
	s_addc_u32 s99, s39, 0
	s_mov_b32 m0, s66
	ds_read_b128 v[198:201], v197 offset:16384
	ds_read_b128 v[202:205], v197 offset:17408
	ds_read_b128 v[206:209], v197 offset:18432
	ds_read_b128 v[210:213], v197 offset:19456
	ds_read_b128 v[214:217], v197 offset:20480
	ds_read_b128 v[218:221], v197 offset:21504
	ds_read_b128 v[222:225], v197 offset:22528
	ds_read_b128 v[226:229], v197 offset:23552
	global_load_lds_dwordx4 v156, s[38:39]
	s_add_i32 m0, s66, 0x2000
	s_add_u32 s66, s38, 0x100000
	s_addc_u32 s67, s39, 0
	s_add_i32 vcc_hi, vcc_hi, s97
	global_load_lds_dwordx4 v160, s[38:39]
	s_mov_b32 m0, vcc_hi
	s_add_u32 s100, s86, 0x80
	s_addc_u32 s101, s87, 0
	global_load_lds_dwordx4 v156, s[66:67]
	s_add_i32 m0, vcc_hi, 0x2000
	s_nop 0
	global_load_lds_dwordx4 v160, s[66:67]
	s_mov_b32 m0, s85
	s_nop 0
	global_load_lds_dwordx4 v154, s[86:87]
	s_mov_b32 m0, s92
	s_nop 0
	global_load_lds_dwordx4 v158, s[86:87]
	s_waitcnt vmcnt(24)
	s_waitcnt lgkmcnt(0)
	s_setprio 1
	s_barrier
	v_mfma_f32_16x16x32_bf16 v[62:65], v[130:133], v[198:201], 0
	v_mfma_f32_16x16x32_bf16 v[58:61], v[138:141], v[198:201], 0
	v_mfma_f32_16x16x32_bf16 v[38:41], v[130:133], v[206:209], 0
	v_mfma_f32_16x16x32_bf16 v[34:37], v[138:141], v[206:209], 0
	v_mfma_f32_16x16x32_bf16 v[22:25], v[130:133], v[214:217], 0
	v_mfma_f32_16x16x32_bf16 v[18:21], v[138:141], v[214:217], 0
	v_mfma_f32_16x16x32_bf16 v[6:9], v[130:133], v[222:225], 0
	v_mfma_f32_16x16x32_bf16 v[2:5], v[138:141], v[222:225], 0
	v_mfma_f32_16x16x32_bf16 v[62:65], v[134:137], v[202:205], v[62:65]
	v_mfma_f32_16x16x32_bf16 v[58:61], v[142:145], v[202:205], v[58:61]
	v_mfma_f32_16x16x32_bf16 v[38:41], v[134:137], v[210:213], v[38:41]
	v_mfma_f32_16x16x32_bf16 v[34:37], v[142:145], v[210:213], v[34:37]
	v_mfma_f32_16x16x32_bf16 v[22:25], v[134:137], v[218:221], v[22:25]
	v_mfma_f32_16x16x32_bf16 v[18:21], v[142:145], v[218:221], v[18:21]
	v_mfma_f32_16x16x32_bf16 v[6:9], v[134:137], v[226:229], v[6:9]
	v_mfma_f32_16x16x32_bf16 v[2:5], v[142:145], v[226:229], v[2:5]
	s_setprio 0
	s_setprio 1
	v_mfma_f32_16x16x32_bf16 v[78:81], v[168:171], v[198:201], 0
	v_mfma_f32_16x16x32_bf16 v[74:77], v[176:179], v[198:201], 0
	v_mfma_f32_16x16x32_bf16 v[46:49], v[168:171], v[206:209], 0
	v_mfma_f32_16x16x32_bf16 v[42:45], v[176:179], v[206:209], 0
	v_mfma_f32_16x16x32_bf16 v[30:33], v[168:171], v[214:217], 0
	v_mfma_f32_16x16x32_bf16 v[26:29], v[176:179], v[214:217], 0
	v_mfma_f32_16x16x32_bf16 v[14:17], v[168:171], v[222:225], 0
	v_mfma_f32_16x16x32_bf16 v[10:13], v[176:179], v[222:225], 0
	v_mfma_f32_16x16x32_bf16 v[78:81], v[172:175], v[202:205], v[78:81]
	v_mfma_f32_16x16x32_bf16 v[74:77], v[180:183], v[202:205], v[74:77]
	v_mfma_f32_16x16x32_bf16 v[46:49], v[172:175], v[210:213], v[46:49]
	v_mfma_f32_16x16x32_bf16 v[42:45], v[180:183], v[210:213], v[42:45]
	v_mfma_f32_16x16x32_bf16 v[30:33], v[172:175], v[218:221], v[30:33]
	v_mfma_f32_16x16x32_bf16 v[26:29], v[180:183], v[218:221], v[26:29]
	v_mfma_f32_16x16x32_bf16 v[14:17], v[172:175], v[226:229], v[14:17]
	v_mfma_f32_16x16x32_bf16 v[10:13], v[180:183], v[226:229], v[10:13]
	s_barrier
	s_setprio 0
	s_add_i32 vcc_hi, 0, 0x18000
	s_add_i32 s56, 0, 0x1c000
	v_add_u32_e32 v142, vcc_hi, v1
	v_add_u32_e32 v180, s56, v1
	ds_read_b128 v[130:133], v142
	ds_read_b128 v[134:137], v142 offset:1024
	ds_read_b128 v[138:141], v142 offset:2048
	ds_read_b128 v[142:145], v142 offset:3072
	ds_read_b128 v[168:171], v180
	ds_read_b128 v[172:175], v180 offset:1024
	ds_read_b128 v[176:179], v180 offset:2048
	ds_read_b128 v[180:183], v180 offset:3072
	s_add_u32 s66, s86, 0x100000
	s_addc_u32 s67, s87, 0
	s_mov_b32 m0, s93
	ds_read_b128 v[198:201], v197 offset:32768
	ds_read_b128 v[202:205], v197 offset:33792
	ds_read_b128 v[206:209], v197 offset:34816
	ds_read_b128 v[210:213], v197 offset:35840
	ds_read_b128 v[214:217], v197 offset:36864
	ds_read_b128 v[218:221], v197 offset:37888
	ds_read_b128 v[222:225], v197 offset:38912
	ds_read_b128 v[226:229], v197 offset:39936
	global_load_lds_dwordx4 v154, s[66:67]
	s_mov_b32 m0, s42
	s_nop 0
	global_load_lds_dwordx4 v158, s[66:67]
	s_waitcnt vmcnt(8)
	s_waitcnt lgkmcnt(0)
	s_setprio 1
	s_barrier
	v_mfma_f32_16x16x32_bf16 v[114:117], v[130:133], v[198:201], v[114:117]
	v_mfma_f32_16x16x32_bf16 v[118:121], v[138:141], v[198:201], v[118:121]
	v_mfma_f32_16x16x32_bf16 v[102:105], v[130:133], v[206:209], v[102:105]
	v_mfma_f32_16x16x32_bf16 v[98:101], v[138:141], v[206:209], v[98:101]
	v_mfma_f32_16x16x32_bf16 v[86:89], v[130:133], v[214:217], v[86:89]
	v_mfma_f32_16x16x32_bf16 v[82:85], v[138:141], v[214:217], v[82:85]
	v_mfma_f32_16x16x32_bf16 v[54:57], v[130:133], v[222:225], v[54:57]
	v_mfma_f32_16x16x32_bf16 v[50:53], v[138:141], v[222:225], v[50:53]
	v_mfma_f32_16x16x32_bf16 v[114:117], v[134:137], v[202:205], v[114:117]
	v_mfma_f32_16x16x32_bf16 v[118:121], v[142:145], v[202:205], v[118:121]
	v_mfma_f32_16x16x32_bf16 v[102:105], v[134:137], v[210:213], v[102:105]
	v_mfma_f32_16x16x32_bf16 v[98:101], v[142:145], v[210:213], v[98:101]
	v_mfma_f32_16x16x32_bf16 v[86:89], v[134:137], v[218:221], v[86:89]
	v_mfma_f32_16x16x32_bf16 v[82:85], v[142:145], v[218:221], v[82:85]
	v_mfma_f32_16x16x32_bf16 v[54:57], v[134:137], v[226:229], v[54:57]
	v_mfma_f32_16x16x32_bf16 v[50:53], v[142:145], v[226:229], v[50:53]
	s_setprio 0
	s_setprio 1
	v_mfma_f32_16x16x32_bf16 v[126:129], v[168:171], v[198:201], v[126:129]
	v_mfma_f32_16x16x32_bf16 v[122:125], v[176:179], v[198:201], v[122:125]
	v_mfma_f32_16x16x32_bf16 v[110:113], v[168:171], v[206:209], v[110:113]
	v_mfma_f32_16x16x32_bf16 v[106:109], v[176:179], v[206:209], v[106:109]
	v_mfma_f32_16x16x32_bf16 v[94:97], v[168:171], v[214:217], v[94:97]
	v_mfma_f32_16x16x32_bf16 v[90:93], v[176:179], v[214:217], v[90:93]
	v_mfma_f32_16x16x32_bf16 v[70:73], v[168:171], v[222:225], v[70:73]
	v_mfma_f32_16x16x32_bf16 v[66:69], v[176:179], v[222:225], v[66:69]
	v_mfma_f32_16x16x32_bf16 v[126:129], v[172:175], v[202:205], v[126:129]
	v_mfma_f32_16x16x32_bf16 v[122:125], v[180:183], v[202:205], v[122:125]
	v_mfma_f32_16x16x32_bf16 v[110:113], v[172:175], v[210:213], v[110:113]
	v_mfma_f32_16x16x32_bf16 v[106:109], v[180:183], v[210:213], v[106:109]
	v_mfma_f32_16x16x32_bf16 v[94:97], v[172:175], v[218:221], v[94:97]
	v_mfma_f32_16x16x32_bf16 v[90:93], v[180:183], v[218:221], v[90:93]
	v_mfma_f32_16x16x32_bf16 v[70:73], v[172:175], v[226:229], v[70:73]
	v_mfma_f32_16x16x32_bf16 v[66:69], v[180:183], v[226:229], v[66:69]
	s_barrier
	s_setprio 0
	s_add_i32 s57, vcc_hi, s97
	s_mov_b32 m0, s57
	ds_read_b128 v[198:201], v197 offset:49152
	ds_read_b128 v[202:205], v197 offset:50176
	ds_read_b128 v[206:209], v197 offset:51200
	ds_read_b128 v[210:213], v197 offset:52224
	ds_read_b128 v[214:217], v197 offset:53248
	ds_read_b128 v[218:221], v197 offset:54272
	ds_read_b128 v[222:225], v197 offset:55296
	ds_read_b128 v[226:229], v197 offset:56320
	global_load_lds_dwordx4 v156, s[98:99]
	s_add_i32 m0, s57, 0x2000
	s_add_u32 s38, s38, 0x100080
	s_addc_u32 s39, s39, 0
	s_add_i32 s56, s56, s97
	global_load_lds_dwordx4 v160, s[98:99]
	s_mov_b32 m0, s56
	s_nop 0
	global_load_lds_dwordx4 v156, s[38:39]
	s_add_i32 m0, s56, 0x2000
	s_nop 0
	global_load_lds_dwordx4 v160, s[38:39]
	s_mov_b32 m0, s43
	s_nop 0
	global_load_lds_dwordx4 v154, s[100:101]
	s_mov_b32 m0, s90
	s_nop 0
	global_load_lds_dwordx4 v158, s[100:101]
	s_waitcnt vmcnt(8)
	s_waitcnt lgkmcnt(0)
	s_setprio 1
	s_barrier
	v_mfma_f32_16x16x32_bf16 v[62:65], v[130:133], v[198:201], v[62:65]
	v_mfma_f32_16x16x32_bf16 v[58:61], v[138:141], v[198:201], v[58:61]
	v_mfma_f32_16x16x32_bf16 v[38:41], v[130:133], v[206:209], v[38:41]
	v_mfma_f32_16x16x32_bf16 v[34:37], v[138:141], v[206:209], v[34:37]
	v_mfma_f32_16x16x32_bf16 v[22:25], v[130:133], v[214:217], v[22:25]
	v_mfma_f32_16x16x32_bf16 v[18:21], v[138:141], v[214:217], v[18:21]
	v_mfma_f32_16x16x32_bf16 v[6:9], v[130:133], v[222:225], v[6:9]
	v_mfma_f32_16x16x32_bf16 v[2:5], v[138:141], v[222:225], v[2:5]
	v_mfma_f32_16x16x32_bf16 v[62:65], v[134:137], v[202:205], v[62:65]
	v_mfma_f32_16x16x32_bf16 v[58:61], v[142:145], v[202:205], v[58:61]
	v_mfma_f32_16x16x32_bf16 v[38:41], v[134:137], v[210:213], v[38:41]
	v_mfma_f32_16x16x32_bf16 v[34:37], v[142:145], v[210:213], v[34:37]
	v_mfma_f32_16x16x32_bf16 v[22:25], v[134:137], v[218:221], v[22:25]
	v_mfma_f32_16x16x32_bf16 v[18:21], v[142:145], v[218:221], v[18:21]
	v_mfma_f32_16x16x32_bf16 v[6:9], v[134:137], v[226:229], v[6:9]
	v_mfma_f32_16x16x32_bf16 v[2:5], v[142:145], v[226:229], v[2:5]
	s_setprio 0
	s_setprio 1
	v_mfma_f32_16x16x32_bf16 v[78:81], v[168:171], v[198:201], v[78:81]
	v_mfma_f32_16x16x32_bf16 v[74:77], v[176:179], v[198:201], v[74:77]
	v_mfma_f32_16x16x32_bf16 v[46:49], v[168:171], v[206:209], v[46:49]
	v_mfma_f32_16x16x32_bf16 v[42:45], v[176:179], v[206:209], v[42:45]
	v_mfma_f32_16x16x32_bf16 v[30:33], v[168:171], v[214:217], v[30:33]
	v_mfma_f32_16x16x32_bf16 v[26:29], v[176:179], v[214:217], v[26:29]
	v_mfma_f32_16x16x32_bf16 v[14:17], v[168:171], v[222:225], v[14:17]
	v_mfma_f32_16x16x32_bf16 v[10:13], v[176:179], v[222:225], v[10:13]
	v_mfma_f32_16x16x32_bf16 v[78:81], v[172:175], v[202:205], v[78:81]
	v_mfma_f32_16x16x32_bf16 v[74:77], v[180:183], v[202:205], v[74:77]
	v_mfma_f32_16x16x32_bf16 v[46:49], v[172:175], v[210:213], v[46:49]
	v_mfma_f32_16x16x32_bf16 v[42:45], v[180:183], v[210:213], v[42:45]
	v_mfma_f32_16x16x32_bf16 v[30:33], v[172:175], v[218:221], v[30:33]
	v_mfma_f32_16x16x32_bf16 v[26:29], v[180:183], v[218:221], v[26:29]
	v_mfma_f32_16x16x32_bf16 v[14:17], v[172:175], v[226:229], v[14:17]
	v_mfma_f32_16x16x32_bf16 v[10:13], v[180:183], v[226:229], v[10:13]
	s_barrier
	s_setprio 0
	s_add_u32 s40, s40, 0x100
	s_addc_u32 s49, s49, 0
	s_add_u32 s10, s10, 0x100
	s_addc_u32 s11, s11, 0
	s_cmp_ge_u32 vcc_lo, s19
	s_mov_b32 s38, vcc_lo
	s_cbranch_scc1 .Lpeel_done_0

.LBB0_1687:
	s_mov_b64 s[0:1], 0x80
	v_lshl_add_u64 v[6:7], v[6:7], 0, s[0:1]
	s_add_i32 m0, s94, 0x18000
	s_waitcnt vmcnt(2)
	s_barrier
	global_load_lds_dwordx4 v[6:7], off
	v_lshl_add_u64 v[4:5], v[4:5], 0, s[0:1]
	s_add_i32 m0, s94, 0x1a000
	s_add_i32 s28, s94, 0x8000
	s_add_i32 s29, s94, 0xa000
	global_load_lds_dwordx4 v[4:5], off
	v_lshl_add_u64 v[0:1], v[0:1], 0, s[0:1]
	s_mov_b32 m0, s28
	s_add_u32 s4, s24, 0x20080
	global_load_lds_dwordx4 v[0:1], off
	v_lshl_add_u64 v[0:1], v[2:3], 0, s[0:1]
	s_mov_b32 m0, s29
	s_addc_u32 s5, s25, 0
	global_load_lds_dwordx4 v[0:1], off
	v_lshl_add_u64 v[0:1], s[4:5], 0, v[148:149]
	s_add_i32 m0, s94, 0x1c000
	v_and_b32_e32 v4, 48, v11
	global_load_lds_dwordx4 v[0:1], off
	v_lshl_add_u64 v[0:1], s[4:5], 0, v[144:145]
	s_add_i32 m0, s94, 0x1e000
	s_movk_i32 s4, 0x3c0
	global_load_lds_dwordx4 v[0:1], off
	v_and_b32_e32 v0, 15, v11
	v_or_b32_e32 v166, s92, v0
	v_lshlrev_b32_e32 v3, 6, v166
	v_ashrrev_i32_e32 v2, 6, v11
	v_and_or_b32 v3, v3, s4, v4
	v_readlane_b32 s4, v254, 39
	v_lshl_or_b32 v0, v0, 6, v4
	v_lshlrev_b32_e32 v4, 2, v11
	v_lshl_add_u32 v5, v2, 10, s4
	v_readlane_b32 s4, v255, 11
	v_and_b32_e32 v4, 32, v4
	v_ashrrev_i32_e32 v1, 1, v11
	v_add_lshl_u32 v2, v2, s4, 10
	v_bitop3_b32 v167, v0, v2, v4 bitop3:0xde
	v_lshlrev_b32_e32 v0, 15, v12
	v_and_b32_e32 v1, -8, v1
	v_readlane_b32 s4, v255, 14
	v_and_b32_e32 v0, 0xffff0000, v0
	v_lshl_add_u32 v0, v13, 12, v0
	v_add_u32_e32 v168, s4, v1
	v_and_b32_e32 v1, 1, v12
	v_lshl_or_b32 v0, v1, 6, v0
	v_lshl_add_u32 v152, v14, 1, v0
	v_lshlrev_b32_e32 v0, 15, v8
	v_lshlrev_b32_e32 v6, 2, v166
	v_and_b32_e32 v0, 0xffff0000, v0
	v_and_b32_e32 v6, 32, v6
	s_waitcnt vmcnt(0)
	v_lshl_add_u32 v0, v9, 12, v0
	v_and_b32_e32 v1, 1, v8
	v_bitop3_b32 v3, v3, v5, v6 bitop3:0xde
	v_lshl_or_b32 v0, v1, 6, v0
	s_add_i32 s31, 0, 0x10000
	s_add_i32 s33, 0, 0x14000
	s_ashr_i32 s30, s2, 31
	v_mov_b32_e32 v153, v149
	v_lshl_add_u32 v154, v10, 1, v0
	v_mov_b32_e32 v155, v149
	v_mov_b64_e32 v[156:157], 0x110
	v_add_u32_e32 v169, s31, v167
	v_add_u32_e32 v170, s33, v167
	v_add_u32_e32 v171, 0, v3
	s_mov_b64 s[4:5], s[22:23]
	s_barrier
	s_branch .LBB0_1690

.LBB0_1692:
	s_ashr_i32 s13, s12, 31
	s_lshl_b64 s[16:17], s[12:13], 18
	s_add_u32 s16, s45, s16
	s_addc_u32 s17, s44, s17
	s_and_b64 s[26:27], s[26:27], exec
	s_cselect_b32 s13, s17, s25
	s_cselect_b32 s15, s16, s24
	s_add_u32 s34, s24, 0x100
	s_addc_u32 s35, s25, 0
	s_add_u32 s22, s22, 0x80080
	s_addc_u32 s23, s23, 0
	s_mov_b32 s36, -2
	ds_read_b128 v[128:131], v169
	ds_read_b128 v[132:135], v169 offset:1024
	ds_read_b128 v[136:139], v169 offset:2048
	ds_read_b128 v[140:143], v169 offset:3072
	ds_read_b128 v[158:161], v170
	ds_read_b128 v[162:165], v170 offset:1024
	ds_read_b128 v[172:175], v170 offset:2048
	ds_read_b128 v[176:179], v170 offset:3072
	s_add_u32 s24, s22, 0xfff80080
	s_addc_u32 s25, s23, -1
	s_cmp_eq_u32 s36, 4
	s_cselect_b32 s27, s5, s25
	s_cselect_b32 s26, s4, s24
	s_cselect_b32 s25, s13, s35
	s_cselect_b32 s24, s15, s34
	s_add_i32 m0, s94, 0xc000
	ds_read_b128 v[180:183], v171
	ds_read_b128 v[184:187], v171 offset:1024
	ds_read_b128 v[188:191], v171 offset:2048
	ds_read_b128 v[192:195], v171 offset:3072
	ds_read_b128 v[196:199], v171 offset:4096
	ds_read_b128 v[200:203], v171 offset:5120
	ds_read_b128 v[204:207], v171 offset:6144
	ds_read_b128 v[208:211], v171 offset:7168
	global_load_lds_dwordx4 v152, s[22:23]
	s_add_i32 m0, s94, 0xe000
	s_nop 0
	global_load_lds_dwordx4 v154, s[22:23]
	s_waitcnt vmcnt(24)
	s_waitcnt lgkmcnt(0)
	s_setprio 1
	s_barrier
	v_mfma_f32_16x16x32_bf16 v[80:83], v[128:131], v[180:183], 0
	v_mfma_f32_16x16x32_bf16 v[92:95], v[136:139], v[180:183], 0
	v_mfma_f32_16x16x32_bf16 v[84:87], v[128:131], v[188:191], 0
	v_mfma_f32_16x16x32_bf16 v[96:99], v[136:139], v[188:191], 0
	v_mfma_f32_16x16x32_bf16 v[88:91], v[128:131], v[196:199], 0
	v_mfma_f32_16x16x32_bf16 v[100:103], v[136:139], v[196:199], 0
	v_mfma_f32_16x16x32_bf16 v[72:75], v[128:131], v[204:207], 0
	v_mfma_f32_16x16x32_bf16 v[76:79], v[136:139], v[204:207], 0
	v_mfma_f32_16x16x32_bf16 v[80:83], v[132:135], v[184:187], v[80:83]
	v_mfma_f32_16x16x32_bf16 v[92:95], v[140:143], v[184:187], v[92:95]
	v_mfma_f32_16x16x32_bf16 v[84:87], v[132:135], v[192:195], v[84:87]
	v_mfma_f32_16x16x32_bf16 v[96:99], v[140:143], v[192:195], v[96:99]
	v_mfma_f32_16x16x32_bf16 v[88:91], v[132:135], v[200:203], v[88:91]
	v_mfma_f32_16x16x32_bf16 v[100:103], v[140:143], v[200:203], v[100:103]
	v_mfma_f32_16x16x32_bf16 v[72:75], v[132:135], v[208:211], v[72:75]
	v_mfma_f32_16x16x32_bf16 v[76:79], v[140:143], v[208:211], v[76:79]
	s_setprio 0
	s_setprio 1
	v_mfma_f32_16x16x32_bf16 v[104:107], v[158:161], v[180:183], 0
	v_mfma_f32_16x16x32_bf16 v[116:119], v[172:175], v[180:183], 0
	v_mfma_f32_16x16x32_bf16 v[108:111], v[158:161], v[188:191], 0
	v_mfma_f32_16x16x32_bf16 v[120:123], v[172:175], v[188:191], 0
	v_mfma_f32_16x16x32_bf16 v[112:115], v[158:161], v[196:199], 0
	v_mfma_f32_16x16x32_bf16 v[124:127], v[172:175], v[196:199], 0
	v_mfma_f32_16x16x32_bf16 v[68:71], v[158:161], v[204:207], 0
	v_mfma_f32_16x16x32_bf16 v[64:67], v[172:175], v[204:207], 0
	v_mfma_f32_16x16x32_bf16 v[104:107], v[162:165], v[184:187], v[104:107]
	v_mfma_f32_16x16x32_bf16 v[116:119], v[176:179], v[184:187], v[116:119]
	v_mfma_f32_16x16x32_bf16 v[108:111], v[162:165], v[192:195], v[108:111]
	v_mfma_f32_16x16x32_bf16 v[120:123], v[176:179], v[192:195], v[120:123]
	v_mfma_f32_16x16x32_bf16 v[112:115], v[162:165], v[200:203], v[112:115]
	v_mfma_f32_16x16x32_bf16 v[124:127], v[176:179], v[200:203], v[124:127]
	v_mfma_f32_16x16x32_bf16 v[68:71], v[162:165], v[208:211], v[68:71]
	v_mfma_f32_16x16x32_bf16 v[64:67], v[176:179], v[208:211], v[64:67]
	s_barrier
	s_setprio 0
	s_add_i32 s37, s31, s97
	s_add_u32 s98, s24, 0x80
	s_addc_u32 s99, s25, 0
	s_mov_b32 m0, s37
	ds_read_b128 v[180:183], v171 offset:16384
	ds_read_b128 v[184:187], v171 offset:17408
	ds_read_b128 v[188:191], v171 offset:18432
	ds_read_b128 v[192:195], v171 offset:19456
	ds_read_b128 v[196:199], v171 offset:20480
	ds_read_b128 v[200:203], v171 offset:21504
	ds_read_b128 v[204:207], v171 offset:22528
	ds_read_b128 v[208:211], v171 offset:23552
	global_load_lds_dwordx4 v148, s[24:25]
	s_add_i32 m0, s37, 0x2000
	s_add_u32 s38, s24, 0x20000
	s_addc_u32 s39, s25, 0
	s_add_i32 s37, s33, s97
	global_load_lds_dwordx4 v144, s[24:25]
	s_mov_b32 m0, s37
	s_add_u32 s100, s26, 0x80
	s_addc_u32 s101, s27, 0
	global_load_lds_dwordx4 v148, s[38:39]
	s_add_i32 m0, s37, 0x2000
	s_nop 0
	global_load_lds_dwordx4 v144, s[38:39]
	s_mov_b32 m0, s94
	s_nop 0
	global_load_lds_dwordx4 v150, s[26:27]
	s_mov_b32 m0, s3
	s_nop 0
	global_load_lds_dwordx4 v146, s[26:27]
	s_waitcnt vmcnt(24)
	s_waitcnt lgkmcnt(0)
	s_setprio 1
	s_barrier
	v_mfma_f32_16x16x32_bf16 v[48:51], v[128:131], v[180:183], 0
	v_mfma_f32_16x16x32_bf16 v[52:55], v[136:139], v[180:183], 0
	v_mfma_f32_16x16x32_bf16 v[32:35], v[128:131], v[188:191], 0
	v_mfma_f32_16x16x32_bf16 v[36:39], v[136:139], v[188:191], 0
	v_mfma_f32_16x16x32_bf16 v[16:19], v[128:131], v[196:199], 0
	v_mfma_f32_16x16x32_bf16 v[20:23], v[136:139], v[196:199], 0
	v_mfma_f32_16x16x32_bf16 v[0:3], v[128:131], v[204:207], 0
	v_mfma_f32_16x16x32_bf16 v[4:7], v[136:139], v[204:207], 0
	v_mfma_f32_16x16x32_bf16 v[48:51], v[132:135], v[184:187], v[48:51]
	v_mfma_f32_16x16x32_bf16 v[52:55], v[140:143], v[184:187], v[52:55]
	v_mfma_f32_16x16x32_bf16 v[32:35], v[132:135], v[192:195], v[32:35]
	v_mfma_f32_16x16x32_bf16 v[36:39], v[140:143], v[192:195], v[36:39]
	v_mfma_f32_16x16x32_bf16 v[16:19], v[132:135], v[200:203], v[16:19]
	v_mfma_f32_16x16x32_bf16 v[20:23], v[140:143], v[200:203], v[20:23]
	v_mfma_f32_16x16x32_bf16 v[0:3], v[132:135], v[208:211], v[0:3]
	v_mfma_f32_16x16x32_bf16 v[4:7], v[140:143], v[208:211], v[4:7]
	s_setprio 0
	s_setprio 1
	v_mfma_f32_16x16x32_bf16 v[56:59], v[158:161], v[180:183], 0
	v_mfma_f32_16x16x32_bf16 v[60:63], v[172:175], v[180:183], 0
	v_mfma_f32_16x16x32_bf16 v[40:43], v[158:161], v[188:191], 0
	v_mfma_f32_16x16x32_bf16 v[44:47], v[172:175], v[188:191], 0
	v_mfma_f32_16x16x32_bf16 v[24:27], v[158:161], v[196:199], 0
	v_mfma_f32_16x16x32_bf16 v[28:31], v[172:175], v[196:199], 0
	v_mfma_f32_16x16x32_bf16 v[8:11], v[158:161], v[204:207], 0
	v_mfma_f32_16x16x32_bf16 v[12:15], v[172:175], v[204:207], 0
	v_mfma_f32_16x16x32_bf16 v[56:59], v[162:165], v[184:187], v[56:59]
	v_mfma_f32_16x16x32_bf16 v[60:63], v[176:179], v[184:187], v[60:63]
	v_mfma_f32_16x16x32_bf16 v[40:43], v[162:165], v[192:195], v[40:43]
	v_mfma_f32_16x16x32_bf16 v[44:47], v[176:179], v[192:195], v[44:47]
	v_mfma_f32_16x16x32_bf16 v[24:27], v[162:165], v[200:203], v[24:27]
	v_mfma_f32_16x16x32_bf16 v[28:31], v[176:179], v[200:203], v[28:31]
	v_mfma_f32_16x16x32_bf16 v[8:11], v[162:165], v[208:211], v[8:11]
	v_mfma_f32_16x16x32_bf16 v[12:15], v[176:179], v[208:211], v[12:15]
	s_barrier
	s_setprio 0
	s_add_i32 s37, 0, 0x18000
	s_add_i32 s38, 0, 0x1c000
	v_add_u32_e32 v140, s37, v167
	v_add_u32_e32 v176, s38, v167
	ds_read_b128 v[128:131], v140
	ds_read_b128 v[132:135], v140 offset:1024
	ds_read_b128 v[136:139], v140 offset:2048
	ds_read_b128 v[140:143], v140 offset:3072
	ds_read_b128 v[158:161], v176
	ds_read_b128 v[162:165], v176 offset:1024
	ds_read_b128 v[172:175], v176 offset:2048
	ds_read_b128 v[176:179], v176 offset:3072
	s_add_u32 s26, s26, 0x80000
	s_addc_u32 s27, s27, 0
	s_mov_b32 m0, s7
	ds_read_b128 v[180:183], v171 offset:32768
	ds_read_b128 v[184:187], v171 offset:33792
	ds_read_b128 v[188:191], v171 offset:34816
	ds_read_b128 v[192:195], v171 offset:35840
	ds_read_b128 v[196:199], v171 offset:36864
	ds_read_b128 v[200:203], v171 offset:37888
	ds_read_b128 v[204:207], v171 offset:38912
	ds_read_b128 v[208:211], v171 offset:39936
	global_load_lds_dwordx4 v150, s[26:27]
	s_mov_b32 m0, s19
	s_nop 0
	global_load_lds_dwordx4 v146, s[26:27]
	s_waitcnt vmcnt(8)
	s_waitcnt lgkmcnt(0)
	s_setprio 1
	s_barrier
	v_mfma_f32_16x16x32_bf16 v[80:83], v[128:131], v[180:183], v[80:83]
	v_mfma_f32_16x16x32_bf16 v[92:95], v[136:139], v[180:183], v[92:95]
	v_mfma_f32_16x16x32_bf16 v[84:87], v[128:131], v[188:191], v[84:87]
	v_mfma_f32_16x16x32_bf16 v[96:99], v[136:139], v[188:191], v[96:99]
	v_mfma_f32_16x16x32_bf16 v[88:91], v[128:131], v[196:199], v[88:91]
	v_mfma_f32_16x16x32_bf16 v[100:103], v[136:139], v[196:199], v[100:103]
	v_mfma_f32_16x16x32_bf16 v[72:75], v[128:131], v[204:207], v[72:75]
	v_mfma_f32_16x16x32_bf16 v[76:79], v[136:139], v[204:207], v[76:79]
	v_mfma_f32_16x16x32_bf16 v[80:83], v[132:135], v[184:187], v[80:83]
	v_mfma_f32_16x16x32_bf16 v[92:95], v[140:143], v[184:187], v[92:95]
	v_mfma_f32_16x16x32_bf16 v[84:87], v[132:135], v[192:195], v[84:87]
	v_mfma_f32_16x16x32_bf16 v[96:99], v[140:143], v[192:195], v[96:99]
	v_mfma_f32_16x16x32_bf16 v[88:91], v[132:135], v[200:203], v[88:91]
	v_mfma_f32_16x16x32_bf16 v[100:103], v[140:143], v[200:203], v[100:103]
	v_mfma_f32_16x16x32_bf16 v[72:75], v[132:135], v[208:211], v[72:75]
	v_mfma_f32_16x16x32_bf16 v[76:79], v[140:143], v[208:211], v[76:79]
	s_setprio 0
	s_setprio 1
	v_mfma_f32_16x16x32_bf16 v[104:107], v[158:161], v[180:183], v[104:107]
	v_mfma_f32_16x16x32_bf16 v[116:119], v[172:175], v[180:183], v[116:119]
	v_mfma_f32_16x16x32_bf16 v[108:111], v[158:161], v[188:191], v[108:111]
	v_mfma_f32_16x16x32_bf16 v[120:123], v[172:175], v[188:191], v[120:123]
	v_mfma_f32_16x16x32_bf16 v[112:115], v[158:161], v[196:199], v[112:115]
	v_mfma_f32_16x16x32_bf16 v[124:127], v[172:175], v[196:199], v[124:127]
	v_mfma_f32_16x16x32_bf16 v[68:71], v[158:161], v[204:207], v[68:71]
	v_mfma_f32_16x16x32_bf16 v[64:67], v[172:175], v[204:207], v[64:67]
	v_mfma_f32_16x16x32_bf16 v[104:107], v[162:165], v[184:187], v[104:107]
	v_mfma_f32_16x16x32_bf16 v[116:119], v[176:179], v[184:187], v[116:119]
	v_mfma_f32_16x16x32_bf16 v[108:111], v[162:165], v[192:195], v[108:111]
	v_mfma_f32_16x16x32_bf16 v[120:123], v[176:179], v[192:195], v[120:123]
	v_mfma_f32_16x16x32_bf16 v[112:115], v[162:165], v[200:203], v[112:115]
	v_mfma_f32_16x16x32_bf16 v[124:127], v[176:179], v[200:203], v[124:127]
	v_mfma_f32_16x16x32_bf16 v[68:71], v[162:165], v[208:211], v[68:71]
	v_mfma_f32_16x16x32_bf16 v[64:67], v[176:179], v[208:211], v[64:67]
	s_barrier
	s_setprio 0
	s_add_i32 s26, s37, s97
	s_mov_b32 m0, s26
	ds_read_b128 v[180:183], v171 offset:49152
	ds_read_b128 v[184:187], v171 offset:50176
	ds_read_b128 v[188:191], v171 offset:51200
	ds_read_b128 v[192:195], v171 offset:52224
	ds_read_b128 v[196:199], v171 offset:53248
	ds_read_b128 v[200:203], v171 offset:54272
	ds_read_b128 v[204:207], v171 offset:55296
	ds_read_b128 v[208:211], v171 offset:56320
	global_load_lds_dwordx4 v148, s[98:99]
	s_add_i32 m0, s26, 0x2000
	s_add_u32 s24, s24, 0x20080
	s_addc_u32 s25, s25, 0
	s_add_i32 s26, s38, s97
	global_load_lds_dwordx4 v144, s[98:99]
	s_mov_b32 m0, s26
	s_nop 0
	global_load_lds_dwordx4 v148, s[24:25]
	s_add_i32 m0, s26, 0x2000
	s_nop 0
	global_load_lds_dwordx4 v144, s[24:25]
	s_mov_b32 m0, s28
	s_nop 0
	global_load_lds_dwordx4 v150, s[100:101]
	s_mov_b32 m0, s29
	s_nop 0
	global_load_lds_dwordx4 v146, s[100:101]
	s_waitcnt vmcnt(8)
	s_waitcnt lgkmcnt(0)
	s_setprio 1
	s_barrier
	v_mfma_f32_16x16x32_bf16 v[48:51], v[128:131], v[180:183], v[48:51]
	v_mfma_f32_16x16x32_bf16 v[52:55], v[136:139], v[180:183], v[52:55]
	v_mfma_f32_16x16x32_bf16 v[32:35], v[128:131], v[188:191], v[32:35]
	v_mfma_f32_16x16x32_bf16 v[36:39], v[136:139], v[188:191], v[36:39]
	v_mfma_f32_16x16x32_bf16 v[16:19], v[128:131], v[196:199], v[16:19]
	v_mfma_f32_16x16x32_bf16 v[20:23], v[136:139], v[196:199], v[20:23]
	v_mfma_f32_16x16x32_bf16 v[0:3], v[128:131], v[204:207], v[0:3]
	v_mfma_f32_16x16x32_bf16 v[4:7], v[136:139], v[204:207], v[4:7]
	v_mfma_f32_16x16x32_bf16 v[48:51], v[132:135], v[184:187], v[48:51]
	v_mfma_f32_16x16x32_bf16 v[52:55], v[140:143], v[184:187], v[52:55]
	v_mfma_f32_16x16x32_bf16 v[32:35], v[132:135], v[192:195], v[32:35]
	v_mfma_f32_16x16x32_bf16 v[36:39], v[140:143], v[192:195], v[36:39]
	v_mfma_f32_16x16x32_bf16 v[16:19], v[132:135], v[200:203], v[16:19]
	v_mfma_f32_16x16x32_bf16 v[20:23], v[140:143], v[200:203], v[20:23]
	v_mfma_f32_16x16x32_bf16 v[0:3], v[132:135], v[208:211], v[0:3]
	v_mfma_f32_16x16x32_bf16 v[4:7], v[140:143], v[208:211], v[4:7]
	s_setprio 0
	s_setprio 1
	v_mfma_f32_16x16x32_bf16 v[56:59], v[158:161], v[180:183], v[56:59]
	v_mfma_f32_16x16x32_bf16 v[60:63], v[172:175], v[180:183], v[60:63]
	v_mfma_f32_16x16x32_bf16 v[40:43], v[158:161], v[188:191], v[40:43]
	v_mfma_f32_16x16x32_bf16 v[44:47], v[172:175], v[188:191], v[44:47]
	v_mfma_f32_16x16x32_bf16 v[24:27], v[158:161], v[196:199], v[24:27]
	v_mfma_f32_16x16x32_bf16 v[28:31], v[172:175], v[196:199], v[28:31]
	v_mfma_f32_16x16x32_bf16 v[8:11], v[158:161], v[204:207], v[8:11]
	v_mfma_f32_16x16x32_bf16 v[12:15], v[172:175], v[204:207], v[12:15]
	v_mfma_f32_16x16x32_bf16 v[56:59], v[162:165], v[184:187], v[56:59]
	v_mfma_f32_16x16x32_bf16 v[60:63], v[176:179], v[184:187], v[60:63]
	v_mfma_f32_16x16x32_bf16 v[40:43], v[162:165], v[192:195], v[40:43]
	v_mfma_f32_16x16x32_bf16 v[44:47], v[176:179], v[192:195], v[44:47]
	v_mfma_f32_16x16x32_bf16 v[24:27], v[162:165], v[200:203], v[24:27]
	v_mfma_f32_16x16x32_bf16 v[28:31], v[176:179], v[200:203], v[28:31]
	v_mfma_f32_16x16x32_bf16 v[8:11], v[162:165], v[208:211], v[8:11]
	v_mfma_f32_16x16x32_bf16 v[12:15], v[176:179], v[208:211], v[12:15]
	s_barrier
	s_setprio 0
	s_add_i32 s36, s36, 2
	s_add_u32 s34, s34, 0x100
	s_addc_u32 s35, s35, 0
	s_add_u32 s22, s22, 0x100
	s_addc_u32 s23, s23, 0
	s_cmp_gt_u32 s36, 5
	s_cbranch_scc1 .Lpeel_done_1

.LBB0_2004:
	s_mov_b64 s[16:17], 0x80
	v_lshl_add_u64 v[6:7], v[6:7], 0, s[16:17]
	s_add_i32 m0, s94, 0x18000
	s_waitcnt vmcnt(2)
	s_barrier
	global_load_lds_dwordx4 v[6:7], off
	v_lshl_add_u64 v[4:5], v[4:5], 0, s[16:17]
	s_add_i32 m0, s94, 0x1a000
	s_add_i32 s54, s94, 0x8000
	s_add_i32 s55, s94, 0xa000
	global_load_lds_dwordx4 v[4:5], off
	v_lshl_add_u64 v[0:1], v[0:1], 0, s[16:17]
	s_mov_b32 m0, s54
	s_add_u32 s8, s44, 0x100080
	global_load_lds_dwordx4 v[0:1], off
	v_lshl_add_u64 v[0:1], v[2:3], 0, s[16:17]
	s_mov_b32 m0, s55
	s_addc_u32 s9, s45, 0
	global_load_lds_dwordx4 v[0:1], off
	v_lshl_add_u64 v[0:1], s[8:9], 0, v[210:211]
	s_add_i32 m0, s94, 0x1c000
	v_or_b32_e32 v242, s92, v240
	global_load_lds_dwordx4 v[0:1], off
	v_lshl_add_u64 v[0:1], s[8:9], 0, v[214:215]
	s_add_i32 m0, s94, 0x1e000
	v_and_b32_e32 v2, 48, v239
	global_load_lds_dwordx4 v[0:1], off
	v_lshlrev_b32_e32 v1, 6, v242
	s_movk_i32 s5, 0x3c0
	v_ashrrev_i32_e32 v0, 6, v239
	v_and_or_b32 v1, v1, s5, v2
	v_readlane_b32 s5, v254, 39
	v_lshlrev_b32_e32 v4, 2, v242
	v_and_b32_e32 v4, 32, v4
	v_lshl_add_u32 v3, v0, 10, s5
	v_bitop3_b32 v3, v1, v3, v4 bitop3:0xde
	v_lshl_or_b32 v1, v240, 6, v2
	v_readlane_b32 s5, v255, 11
	v_lshlrev_b32_e32 v2, 2, v240
	v_and_b32_e32 v2, 32, v2
	v_add_lshl_u32 v0, v0, s5, 10
	v_bitop3_b32 v243, v1, v0, v2 bitop3:0xde
	v_add_u32_e32 v0, s97, v239
	v_readlane_b32 s18, v254, 63
	v_ashrrev_i32_e32 v1, 31, v0
	v_readlane_b32 s19, v255, 0
	v_readlane_b32 s5, v254, 57
	s_lshr_b32 s5, s5, 29
	v_lshl_add_u64 v[216:217], v[0:1], 4, s[18:19]
	v_cndmask_b32_e64 v0, 0, -1, s[12:13]
	v_and_b32_e32 v1, 1, v8
	v_readfirstlane_b32 s56, v0
	v_lshlrev_b32_e32 v0, 16, v8
	v_and_b32_e32 v0, 0xfffe0000, v0
	v_lshl_add_u32 v0, v9, 13, v0
	s_add_i32 s5, s91, s5
	v_lshl_or_b32 v0, v1, 6, v0
	s_ashr_i32 s59, s5, 3
	s_and_b32 s5, s5, 0x1ffffff8
	v_lshl_add_u32 v218, v10, 1, v0
	v_lshlrev_b32_e32 v0, 16, v11
	s_sub_i32 s5, s91, s5
	v_and_b32_e32 v0, 0xfffe0000, v0
	s_waitcnt vmcnt(0)
	s_lshl_b32 s18, s5, 3
	v_lshl_add_u32 v0, v12, 13, v0
	v_and_b32_e32 v1, 1, v11
	s_mov_b32 s15, 0
	s_ashr_i32 s19, s18, 31
	v_lshl_or_b32 v0, v1, 6, v0
	s_add_i32 s60, 0, 0x10000
	s_add_i32 s61, 0, 0x14000
	v_cmp_lt_u32_e64 s[8:9], 15, v239
	v_cmp_eq_u32_e64 s[10:11], 0, v239
	s_addk_i32 s59, 0x200
	s_lshl_b64 s[18:19], s[18:19], 7
	v_mov_b32_e32 v219, v211
	v_lshl_add_u32 v220, v13, 1, v0
	v_mov_b32_e32 v221, v211
	v_add_u32_e32 v244, s60, v243
	v_add_u32_e32 v245, s61, v243
	v_add_u32_e32 v246, 0, v3
	s_mov_b32 s5, s15
	s_barrier
	s_branch .LBB0_2007

.LBB0_2019:
	s_cmp_lt_u32 s5, 0x3fffffff
	s_cselect_b64 s[40:41], -1, 0
	s_ashr_i32 s23, s22, 31
	s_and_b64 s[40:41], s[36:37], s[40:41]
	s_lshl_b64 s[36:37], s[22:23], 21
	s_add_u32 s5, s86, s36
	s_addc_u32 s21, s87, s37
	s_add_u32 s36, s5, s38
	s_addc_u32 s37, s21, s39
	s_and_b64 s[48:49], s[40:41], exec
	s_cselect_b32 s5, s37, s47
	s_cselect_b32 s23, s36, s46
	s_ashr_i32 s21, s20, 31
	s_lshl_b64 s[48:49], s[20:21], 21
	v_readlane_b32 s68, v254, 13
	v_readlane_b32 s69, v254, 14
	s_add_u32 s21, s68, s48
	s_addc_u32 s43, s69, s49
	s_add_u32 s38, s21, s38
	s_addc_u32 s39, s43, s39
	s_and_b64 s[48:49], s[40:41], exec
	s_cselect_b32 s21, s39, s45
	s_cselect_b32 s43, s38, s44
	s_add_i32 s68, s67, -2
	s_add_u32 s69, s44, 0x100
	s_addc_u32 s70, s45, 0
	s_add_u32 s44, s46, 0x100080
	s_addc_u32 s45, s47, 0
	s_mov_b32 s46, 0
	s_waitcnt vmcnt(0)
	ds_read_b128 v[128:131], v244
	ds_read_b128 v[132:135], v244 offset:1024
	ds_read_b128 v[136:139], v244 offset:2048
	ds_read_b128 v[140:143], v244 offset:3072
	ds_read_b128 v[144:147], v245
	ds_read_b128 v[148:151], v245 offset:1024
	ds_read_b128 v[152:155], v245 offset:2048
	ds_read_b128 v[156:159], v245 offset:3072
	s_add_i32 s71, s46, 2
	s_add_u32 s47, s44, 0xfff00080
	s_addc_u32 s48, s45, -1
	s_cmp_eq_u32 s68, s46
	s_cselect_b32 s46, s43, s69
	s_cselect_b32 s49, s5, s48
	s_cselect_b32 s48, s23, s47
	s_cselect_b32 s47, s21, s70
	s_add_i32 m0, s94, 0xc000
	ds_read_b128 v[160:163], v246
	ds_read_b128 v[164:167], v246 offset:1024
	ds_read_b128 v[168:171], v246 offset:2048
	ds_read_b128 v[172:175], v246 offset:3072
	ds_read_b128 v[176:179], v246 offset:4096
	ds_read_b128 v[180:183], v246 offset:5120
	ds_read_b128 v[184:187], v246 offset:6144
	ds_read_b128 v[188:191], v246 offset:7168
	global_load_lds_dwordx4 v218, s[44:45]
	s_add_i32 m0, s94, 0xe000
	s_nop 0
	global_load_lds_dwordx4 v220, s[44:45]
	s_waitcnt vmcnt(24)
	s_waitcnt lgkmcnt(0)
	s_setprio 1
	s_barrier
	v_mfma_f32_16x16x32_bf16 v[112:115], v[128:131], v[160:163], 0
	v_mfma_f32_16x16x32_bf16 v[116:119], v[136:139], v[160:163], 0
	v_mfma_f32_16x16x32_bf16 v[100:103], v[128:131], v[168:171], 0
	v_mfma_f32_16x16x32_bf16 v[96:99], v[136:139], v[168:171], 0
	v_mfma_f32_16x16x32_bf16 v[84:87], v[128:131], v[176:179], 0
	v_mfma_f32_16x16x32_bf16 v[80:83], v[136:139], v[176:179], 0
	v_mfma_f32_16x16x32_bf16 v[52:55], v[128:131], v[184:187], 0
	v_mfma_f32_16x16x32_bf16 v[48:51], v[136:139], v[184:187], 0
	v_mfma_f32_16x16x32_bf16 v[112:115], v[132:135], v[164:167], v[112:115]
	v_mfma_f32_16x16x32_bf16 v[116:119], v[140:143], v[164:167], v[116:119]
	v_mfma_f32_16x16x32_bf16 v[100:103], v[132:135], v[172:175], v[100:103]
	v_mfma_f32_16x16x32_bf16 v[96:99], v[140:143], v[172:175], v[96:99]
	v_mfma_f32_16x16x32_bf16 v[84:87], v[132:135], v[180:183], v[84:87]
	v_mfma_f32_16x16x32_bf16 v[80:83], v[140:143], v[180:183], v[80:83]
	v_mfma_f32_16x16x32_bf16 v[52:55], v[132:135], v[188:191], v[52:55]
	v_mfma_f32_16x16x32_bf16 v[48:51], v[140:143], v[188:191], v[48:51]
	s_setprio 0
	s_setprio 1
	v_mfma_f32_16x16x32_bf16 v[124:127], v[144:147], v[160:163], 0
	v_mfma_f32_16x16x32_bf16 v[120:123], v[152:155], v[160:163], 0
	v_mfma_f32_16x16x32_bf16 v[108:111], v[144:147], v[168:171], 0
	v_mfma_f32_16x16x32_bf16 v[104:107], v[152:155], v[168:171], 0
	v_mfma_f32_16x16x32_bf16 v[92:95], v[144:147], v[176:179], 0
	v_mfma_f32_16x16x32_bf16 v[88:91], v[152:155], v[176:179], 0
	v_mfma_f32_16x16x32_bf16 v[68:71], v[144:147], v[184:187], 0
	v_mfma_f32_16x16x32_bf16 v[64:67], v[152:155], v[184:187], 0
	v_mfma_f32_16x16x32_bf16 v[124:127], v[148:151], v[164:167], v[124:127]
	v_mfma_f32_16x16x32_bf16 v[120:123], v[156:159], v[164:167], v[120:123]
	v_mfma_f32_16x16x32_bf16 v[108:111], v[148:151], v[172:175], v[108:111]
	v_mfma_f32_16x16x32_bf16 v[104:107], v[156:159], v[172:175], v[104:107]
	v_mfma_f32_16x16x32_bf16 v[92:95], v[148:151], v[180:183], v[92:95]
	v_mfma_f32_16x16x32_bf16 v[88:91], v[156:159], v[180:183], v[88:91]
	v_mfma_f32_16x16x32_bf16 v[68:71], v[148:151], v[188:191], v[68:71]
	v_mfma_f32_16x16x32_bf16 v[64:67], v[156:159], v[188:191], v[64:67]
	s_barrier
	s_setprio 0
	s_add_i32 s76, s60, s97
	s_add_u32 s98, s46, 0x80
	s_addc_u32 s99, s47, 0
	s_mov_b32 m0, s76
	ds_read_b128 v[160:163], v246 offset:16384
	ds_read_b128 v[164:167], v246 offset:17408
	ds_read_b128 v[168:171], v246 offset:18432
	ds_read_b128 v[172:175], v246 offset:19456
	ds_read_b128 v[176:179], v246 offset:20480
	ds_read_b128 v[180:183], v246 offset:21504
	ds_read_b128 v[184:187], v246 offset:22528
	ds_read_b128 v[188:191], v246 offset:23552
	global_load_lds_dwordx4 v210, s[46:47]
	s_add_i32 m0, s76, 0x2000
	s_add_u32 s76, s46, 0x100000
	s_addc_u32 s77, s47, 0
	s_add_i32 s78, s61, s97
	global_load_lds_dwordx4 v214, s[46:47]
	s_mov_b32 m0, s78
	s_add_u32 s100, s48, 0x80
	s_addc_u32 s101, s49, 0
	global_load_lds_dwordx4 v210, s[76:77]
	s_add_i32 m0, s78, 0x2000
	s_nop 0
	global_load_lds_dwordx4 v214, s[76:77]
	s_mov_b32 m0, s94
	s_nop 0
	global_load_lds_dwordx4 v208, s[48:49]
	s_mov_b32 m0, s2
	s_nop 0
	global_load_lds_dwordx4 v212, s[48:49]
	s_waitcnt vmcnt(24)
	s_waitcnt lgkmcnt(0)
	s_setprio 1
	s_barrier
	v_mfma_f32_16x16x32_bf16 v[60:63], v[128:131], v[160:163], 0
	v_mfma_f32_16x16x32_bf16 v[56:59], v[136:139], v[160:163], 0
	v_mfma_f32_16x16x32_bf16 v[36:39], v[128:131], v[168:171], 0
	v_mfma_f32_16x16x32_bf16 v[32:35], v[136:139], v[168:171], 0
	v_mfma_f32_16x16x32_bf16 v[20:23], v[128:131], v[176:179], 0
	v_mfma_f32_16x16x32_bf16 v[16:19], v[136:139], v[176:179], 0
	v_mfma_f32_16x16x32_bf16 v[4:7], v[128:131], v[184:187], 0
	v_mfma_f32_16x16x32_bf16 v[0:3], v[136:139], v[184:187], 0
	v_mfma_f32_16x16x32_bf16 v[60:63], v[132:135], v[164:167], v[60:63]
	v_mfma_f32_16x16x32_bf16 v[56:59], v[140:143], v[164:167], v[56:59]
	v_mfma_f32_16x16x32_bf16 v[36:39], v[132:135], v[172:175], v[36:39]
	v_mfma_f32_16x16x32_bf16 v[32:35], v[140:143], v[172:175], v[32:35]
	v_mfma_f32_16x16x32_bf16 v[20:23], v[132:135], v[180:183], v[20:23]
	v_mfma_f32_16x16x32_bf16 v[16:19], v[140:143], v[180:183], v[16:19]
	v_mfma_f32_16x16x32_bf16 v[4:7], v[132:135], v[188:191], v[4:7]
	v_mfma_f32_16x16x32_bf16 v[0:3], v[140:143], v[188:191], v[0:3]
	s_setprio 0
	s_setprio 1
	v_mfma_f32_16x16x32_bf16 v[76:79], v[144:147], v[160:163], 0
	v_mfma_f32_16x16x32_bf16 v[72:75], v[152:155], v[160:163], 0
	v_mfma_f32_16x16x32_bf16 v[44:47], v[144:147], v[168:171], 0
	v_mfma_f32_16x16x32_bf16 v[40:43], v[152:155], v[168:171], 0
	v_mfma_f32_16x16x32_bf16 v[28:31], v[144:147], v[176:179], 0
	v_mfma_f32_16x16x32_bf16 v[24:27], v[152:155], v[176:179], 0
	v_mfma_f32_16x16x32_bf16 v[12:15], v[144:147], v[184:187], 0
	v_mfma_f32_16x16x32_bf16 v[8:11], v[152:155], v[184:187], 0
	v_mfma_f32_16x16x32_bf16 v[76:79], v[148:151], v[164:167], v[76:79]
	v_mfma_f32_16x16x32_bf16 v[72:75], v[156:159], v[164:167], v[72:75]
	v_mfma_f32_16x16x32_bf16 v[44:47], v[148:151], v[172:175], v[44:47]
	v_mfma_f32_16x16x32_bf16 v[40:43], v[156:159], v[172:175], v[40:43]
	v_mfma_f32_16x16x32_bf16 v[28:31], v[148:151], v[180:183], v[28:31]
	v_mfma_f32_16x16x32_bf16 v[24:27], v[156:159], v[180:183], v[24:27]
	v_mfma_f32_16x16x32_bf16 v[12:15], v[148:151], v[188:191], v[12:15]
	v_mfma_f32_16x16x32_bf16 v[8:11], v[156:159], v[188:191], v[8:11]
	s_barrier
	s_setprio 0
	s_add_i32 s76, 0, 0x18000
	s_add_i32 s77, 0, 0x1c000
	v_add_u32_e32 v140, s76, v243
	v_add_u32_e32 v156, s77, v243
	ds_read_b128 v[128:131], v140
	ds_read_b128 v[132:135], v140 offset:1024
	ds_read_b128 v[136:139], v140 offset:2048
	ds_read_b128 v[140:143], v140 offset:3072
	ds_read_b128 v[144:147], v156
	ds_read_b128 v[148:151], v156 offset:1024
	ds_read_b128 v[152:155], v156 offset:2048
	ds_read_b128 v[156:159], v156 offset:3072
	s_add_u32 s48, s48, 0x100000
	s_addc_u32 s49, s49, 0
	s_mov_b32 m0, s3
	ds_read_b128 v[160:163], v246 offset:32768
	ds_read_b128 v[164:167], v246 offset:33792
	ds_read_b128 v[168:171], v246 offset:34816
	ds_read_b128 v[172:175], v246 offset:35840
	ds_read_b128 v[176:179], v246 offset:36864
	ds_read_b128 v[180:183], v246 offset:37888
	ds_read_b128 v[184:187], v246 offset:38912
	ds_read_b128 v[188:191], v246 offset:39936
	global_load_lds_dwordx4 v208, s[48:49]
	s_mov_b32 m0, s33
	s_nop 0
	global_load_lds_dwordx4 v212, s[48:49]
	s_waitcnt vmcnt(8)
	s_waitcnt lgkmcnt(0)
	s_setprio 1
	s_barrier
	v_mfma_f32_16x16x32_bf16 v[112:115], v[128:131], v[160:163], v[112:115]
	v_mfma_f32_16x16x32_bf16 v[116:119], v[136:139], v[160:163], v[116:119]
	v_mfma_f32_16x16x32_bf16 v[100:103], v[128:131], v[168:171], v[100:103]
	v_mfma_f32_16x16x32_bf16 v[96:99], v[136:139], v[168:171], v[96:99]
	v_mfma_f32_16x16x32_bf16 v[84:87], v[128:131], v[176:179], v[84:87]
	v_mfma_f32_16x16x32_bf16 v[80:83], v[136:139], v[176:179], v[80:83]
	v_mfma_f32_16x16x32_bf16 v[52:55], v[128:131], v[184:187], v[52:55]
	v_mfma_f32_16x16x32_bf16 v[48:51], v[136:139], v[184:187], v[48:51]
	v_mfma_f32_16x16x32_bf16 v[112:115], v[132:135], v[164:167], v[112:115]
	v_mfma_f32_16x16x32_bf16 v[116:119], v[140:143], v[164:167], v[116:119]
	v_mfma_f32_16x16x32_bf16 v[100:103], v[132:135], v[172:175], v[100:103]
	v_mfma_f32_16x16x32_bf16 v[96:99], v[140:143], v[172:175], v[96:99]
	v_mfma_f32_16x16x32_bf16 v[84:87], v[132:135], v[180:183], v[84:87]
	v_mfma_f32_16x16x32_bf16 v[80:83], v[140:143], v[180:183], v[80:83]
	v_mfma_f32_16x16x32_bf16 v[52:55], v[132:135], v[188:191], v[52:55]
	v_mfma_f32_16x16x32_bf16 v[48:51], v[140:143], v[188:191], v[48:51]
	s_setprio 0
	s_setprio 1
	v_mfma_f32_16x16x32_bf16 v[124:127], v[144:147], v[160:163], v[124:127]
	v_mfma_f32_16x16x32_bf16 v[120:123], v[152:155], v[160:163], v[120:123]
	v_mfma_f32_16x16x32_bf16 v[108:111], v[144:147], v[168:171], v[108:111]
	v_mfma_f32_16x16x32_bf16 v[104:107], v[152:155], v[168:171], v[104:107]
	v_mfma_f32_16x16x32_bf16 v[92:95], v[144:147], v[176:179], v[92:95]
	v_mfma_f32_16x16x32_bf16 v[88:91], v[152:155], v[176:179], v[88:91]
	v_mfma_f32_16x16x32_bf16 v[68:71], v[144:147], v[184:187], v[68:71]
	v_mfma_f32_16x16x32_bf16 v[64:67], v[152:155], v[184:187], v[64:67]
	v_mfma_f32_16x16x32_bf16 v[124:127], v[148:151], v[164:167], v[124:127]
	v_mfma_f32_16x16x32_bf16 v[120:123], v[156:159], v[164:167], v[120:123]
	v_mfma_f32_16x16x32_bf16 v[108:111], v[148:151], v[172:175], v[108:111]
	v_mfma_f32_16x16x32_bf16 v[104:107], v[156:159], v[172:175], v[104:107]
	v_mfma_f32_16x16x32_bf16 v[92:95], v[148:151], v[180:183], v[92:95]
	v_mfma_f32_16x16x32_bf16 v[88:91], v[156:159], v[180:183], v[88:91]
	v_mfma_f32_16x16x32_bf16 v[68:71], v[148:151], v[188:191], v[68:71]
	v_mfma_f32_16x16x32_bf16 v[64:67], v[156:159], v[188:191], v[64:67]
	s_barrier
	s_setprio 0
	s_add_i32 s48, s76, s97
	s_mov_b32 m0, s48
	ds_read_b128 v[160:163], v246 offset:49152
	ds_read_b128 v[164:167], v246 offset:50176
	ds_read_b128 v[168:171], v246 offset:51200
	ds_read_b128 v[172:175], v246 offset:52224
	ds_read_b128 v[176:179], v246 offset:53248
	ds_read_b128 v[180:183], v246 offset:54272
	ds_read_b128 v[184:187], v246 offset:55296
	ds_read_b128 v[188:191], v246 offset:56320
	global_load_lds_dwordx4 v210, s[98:99]
	s_add_i32 m0, s48, 0x2000
	s_add_u32 s46, s46, 0x100080
	s_addc_u32 s47, s47, 0
	s_add_i32 s48, s77, s97
	global_load_lds_dwordx4 v214, s[98:99]
	s_mov_b32 m0, s48
	s_nop 0
	global_load_lds_dwordx4 v210, s[46:47]
	s_add_i32 m0, s48, 0x2000
	s_nop 0
	global_load_lds_dwordx4 v214, s[46:47]
	s_mov_b32 m0, s54
	s_nop 0
	global_load_lds_dwordx4 v208, s[100:101]
	s_mov_b32 m0, s55
	s_nop 0
	global_load_lds_dwordx4 v212, s[100:101]
	s_waitcnt vmcnt(8)
	s_waitcnt lgkmcnt(0)
	s_setprio 1
	s_barrier
	v_mfma_f32_16x16x32_bf16 v[60:63], v[128:131], v[160:163], v[60:63]
	v_mfma_f32_16x16x32_bf16 v[56:59], v[136:139], v[160:163], v[56:59]
	v_mfma_f32_16x16x32_bf16 v[36:39], v[128:131], v[168:171], v[36:39]
	v_mfma_f32_16x16x32_bf16 v[32:35], v[136:139], v[168:171], v[32:35]
	v_mfma_f32_16x16x32_bf16 v[20:23], v[128:131], v[176:179], v[20:23]
	v_mfma_f32_16x16x32_bf16 v[16:19], v[136:139], v[176:179], v[16:19]
	v_mfma_f32_16x16x32_bf16 v[4:7], v[128:131], v[184:187], v[4:7]
	v_mfma_f32_16x16x32_bf16 v[0:3], v[136:139], v[184:187], v[0:3]
	v_mfma_f32_16x16x32_bf16 v[60:63], v[132:135], v[164:167], v[60:63]
	v_mfma_f32_16x16x32_bf16 v[56:59], v[140:143], v[164:167], v[56:59]
	v_mfma_f32_16x16x32_bf16 v[36:39], v[132:135], v[172:175], v[36:39]
	v_mfma_f32_16x16x32_bf16 v[32:35], v[140:143], v[172:175], v[32:35]
	v_mfma_f32_16x16x32_bf16 v[20:23], v[132:135], v[180:183], v[20:23]
	v_mfma_f32_16x16x32_bf16 v[16:19], v[140:143], v[180:183], v[16:19]
	v_mfma_f32_16x16x32_bf16 v[4:7], v[132:135], v[188:191], v[4:7]
	v_mfma_f32_16x16x32_bf16 v[0:3], v[140:143], v[188:191], v[0:3]
	s_setprio 0
	s_setprio 1
	v_mfma_f32_16x16x32_bf16 v[76:79], v[144:147], v[160:163], v[76:79]
	v_mfma_f32_16x16x32_bf16 v[72:75], v[152:155], v[160:163], v[72:75]
	v_mfma_f32_16x16x32_bf16 v[44:47], v[144:147], v[168:171], v[44:47]
	v_mfma_f32_16x16x32_bf16 v[40:43], v[152:155], v[168:171], v[40:43]
	v_mfma_f32_16x16x32_bf16 v[28:31], v[144:147], v[176:179], v[28:31]
	v_mfma_f32_16x16x32_bf16 v[24:27], v[152:155], v[176:179], v[24:27]
	v_mfma_f32_16x16x32_bf16 v[12:15], v[144:147], v[184:187], v[12:15]
	v_mfma_f32_16x16x32_bf16 v[8:11], v[152:155], v[184:187], v[8:11]
	v_mfma_f32_16x16x32_bf16 v[76:79], v[148:151], v[164:167], v[76:79]
	v_mfma_f32_16x16x32_bf16 v[72:75], v[156:159], v[164:167], v[72:75]
	v_mfma_f32_16x16x32_bf16 v[44:47], v[148:151], v[172:175], v[44:47]
	v_mfma_f32_16x16x32_bf16 v[40:43], v[156:159], v[172:175], v[40:43]
	v_mfma_f32_16x16x32_bf16 v[28:31], v[148:151], v[180:183], v[28:31]
	v_mfma_f32_16x16x32_bf16 v[24:27], v[156:159], v[180:183], v[24:27]
	v_mfma_f32_16x16x32_bf16 v[12:15], v[148:151], v[188:191], v[12:15]
	v_mfma_f32_16x16x32_bf16 v[8:11], v[156:159], v[188:191], v[8:11]
	s_barrier
	s_setprio 0
	s_add_u32 s69, s69, 0x100
	s_addc_u32 s70, s70, 0
	s_add_u32 s44, s44, 0x100
	s_addc_u32 s45, s45, 0
	s_cmp_ge_u32 s71, s67
	s_mov_b32 s46, s71
	s_cbranch_scc1 .Lpeel_done_2

.LBB0_2269:
	v_readlane_b32 s4, v254, 4
	v_readlane_b32 s5, v254, 5
	s_mov_b32 s8, s4
	s_ashr_i32 s9, s4, 31
	s_lshl_b64 s[4:5], s[8:9], 2
	s_add_u32 s4, s34, s4
	s_addc_u32 s5, s35, s5
	s_lshl_b32 s8, s8, 2
	s_add_i32 s9, 0, 0x20000
	s_mov_b64 s[18:19], 0x80
	s_add_i32 s55, s9, s8
	s_lshl_b32 s8, s92, 2
	v_lshl_add_u64 v[6:7], v[6:7], 0, s[18:19]
	s_add_i32 m0, s94, 0x18000
	s_add_i32 s10, s9, s8
	s_waitcnt vmcnt(2)
	s_barrier
	global_load_lds_dwordx4 v[6:7], off
	v_lshl_add_u64 v[4:5], v[4:5], 0, s[18:19]
	s_add_i32 m0, s94, 0x1a000
	s_add_i32 s68, s94, 0x8000
	s_add_i32 s69, s94, 0xa000
	global_load_lds_dwordx4 v[4:5], off
	v_lshl_add_u64 v[0:1], v[0:1], 0, s[18:19]
	s_mov_b32 m0, s68
	s_add_u32 s8, s44, 0x100080
	global_load_lds_dwordx4 v[0:1], off
	v_lshl_add_u64 v[0:1], v[2:3], 0, s[18:19]
	s_mov_b32 m0, s69
	s_addc_u32 s9, s45, 0
	global_load_lds_dwordx4 v[0:1], off
	v_lshl_add_u64 v[0:1], s[8:9], 0, v[132:133]
	s_add_i32 m0, s94, 0x1c000
	v_or_b32_e32 v156, s92, v154
	global_load_lds_dwordx4 v[0:1], off
	v_lshl_add_u64 v[0:1], s[8:9], 0, v[136:137]
	s_add_i32 m0, s94, 0x1e000
	v_and_b32_e32 v2, 48, v128
	global_load_lds_dwordx4 v[0:1], off
	v_lshlrev_b32_e32 v1, 6, v156
	s_movk_i32 s8, 0x3c0
	v_ashrrev_i32_e32 v0, 6, v128
	v_and_or_b32 v1, v1, s8, v2
	v_readlane_b32 s8, v254, 39
	v_lshlrev_b32_e32 v4, 2, v156
	v_and_b32_e32 v4, 32, v4
	v_lshl_add_u32 v3, v0, 10, s8
	v_bitop3_b32 v3, v1, v3, v4 bitop3:0xde
	v_lshl_or_b32 v1, v154, 6, v2
	v_readlane_b32 s8, v255, 11
	v_lshlrev_b32_e32 v2, 2, v154
	v_and_b32_e32 v4, 32, v2
	v_add_lshl_u32 v0, v0, s8, 10
	v_ashrrev_i32_e32 v129, 31, v128
	v_bitop3_b32 v157, v1, v0, v4 bitop3:0xde
	v_add_u32_e32 v0, s97, v128
	v_lshl_add_u64 v[138:139], v[128:129], 2, s[4:5]
	v_readlane_b32 s4, v254, 63
	v_ashrrev_i32_e32 v1, 31, v0
	v_readlane_b32 s5, v255, 0
	s_waitcnt vmcnt(0)
	s_add_i32 s77, 0, 0x10000
	s_add_i32 s78, 0, 0x14000
	v_lshl_add_u64 v[140:141], v[0:1], 4, s[4:5]
	v_cndmask_b32_e64 v0, 0, -1, s[12:13]
	s_lshr_b32 s4, s91, 31
	v_readfirstlane_b32 s71, v0
	v_lshlrev_b32_e32 v0, 16, v8
	s_add_i32 s4, s91, s4
	v_and_b32_e32 v0, 0xfffe0000, v0
	s_ashr_i32 s76, s4, 1
	s_and_b32 s4, s4, 0x7fffffe
	v_lshl_add_u32 v0, v9, 13, v0
	v_and_b32_e32 v1, 1, v8
	s_sub_i32 s4, s91, s4
	v_lshl_or_b32 v0, v1, 6, v0
	s_lshl_b32 s4, s4, 5
	v_lshl_add_u32 v142, v10, 1, v0
	v_lshlrev_b32_e32 v0, 16, v11
	s_ashr_i32 s5, s4, 31
	v_and_b32_e32 v0, 0xfffe0000, v0
	s_lshl_b64 s[20:21], s[4:5], 7
	v_lshl_add_u32 v0, v12, 13, v0
	v_and_b32_e32 v1, 1, v11
	v_readlane_b32 s4, v254, 27
	v_lshl_or_b32 v0, v1, 6, v0
	v_readlane_b32 s5, v254, 28
	s_mov_b32 s15, s17
	v_readfirstlane_b32 s70, v238
	v_add_u32_e32 v158, s95, v155
	v_cmp_eq_u32_e64 s[8:9], 0, v128
	v_add_u32_e32 v129, s10, v2
	s_addk_i32 s76, 0x800
	v_mov_b32_e32 v143, v133
	v_lshl_add_u32 v144, v13, 1, v0
	v_mov_b32_e32 v145, v133
	s_xor_b64 s[22:23], s[4:5], -1
	v_add_u32_e32 v159, s77, v157
	v_add_u32_e32 v160, s78, v157
	v_add_u32_e32 v161, 0, v3
	v_mov_b32_e32 v162, 0x358637bd
	v_mov_b64_e32 v[146:147], 0x880
	s_mov_b32 s41, s17
	s_barrier
	s_branch .LBB0_2272

.LBB0_2288:
	s_ashr_i32 s25, s24, 31
	s_lshl_b64 s[86:87], s[24:25], 21
	v_readlane_b32 s88, v254, 52
	v_readlane_b32 s89, v254, 53
	s_add_u32 s5, s88, s86
	s_addc_u32 s25, s89, s87
	s_add_u32 s38, s5, s38
	s_addc_u32 s39, s25, s39
	s_and_b64 s[48:49], s[48:49], exec
	s_cselect_b32 s5, s39, s45
	s_cselect_b32 s25, s38, s44
	s_add_i32 s43, s84, -2
	s_add_u32 s85, s44, 0x100
	s_addc_u32 s86, s45, 0
	s_add_u32 s44, s46, 0x100080
	s_addc_u32 s45, s47, 0
	s_mov_b32 s46, 0
	ds_read_b128 v[148:151], v159
	ds_read_b128 v[164:167], v159 offset:1024
	ds_read_b128 v[168:171], v159 offset:2048
	ds_read_b128 v[172:175], v159 offset:3072
	ds_read_b128 v[176:179], v160
	ds_read_b128 v[180:183], v160 offset:1024
	ds_read_b128 v[184:187], v160 offset:2048
	ds_read_b128 v[188:191], v160 offset:3072
	s_add_i32 s87, s46, 2
	s_add_u32 s47, s44, 0xfff00080
	s_addc_u32 s48, s45, -1
	s_cmp_eq_u32 s43, s46
	s_cselect_b32 s46, s25, s85
	s_cselect_b32 s49, s37, s48
	s_cselect_b32 s48, s36, s47
	s_cselect_b32 s47, s5, s86
	s_add_i32 m0, s94, 0xc000
	ds_read_b128 v[192:195], v161
	ds_read_b128 v[196:199], v161 offset:1024
	ds_read_b128 v[200:203], v161 offset:2048
	ds_read_b128 v[204:207], v161 offset:3072
	ds_read_b128 v[208:211], v161 offset:4096
	ds_read_b128 v[212:215], v161 offset:5120
	ds_read_b128 v[216:219], v161 offset:6144
	ds_read_b128 v[220:223], v161 offset:7168
	global_load_lds_dwordx4 v142, s[44:45]
	s_add_i32 m0, s94, 0xe000
	s_nop 0
	global_load_lds_dwordx4 v144, s[44:45]
	s_waitcnt vmcnt(24)
	s_waitcnt lgkmcnt(0)
	s_setprio 1
	s_barrier
	v_mfma_f32_16x16x32_bf16 v[112:115], v[148:151], v[192:195], 0
	v_mfma_f32_16x16x32_bf16 v[116:119], v[168:171], v[192:195], 0
	v_mfma_f32_16x16x32_bf16 v[100:103], v[148:151], v[200:203], 0
	v_mfma_f32_16x16x32_bf16 v[96:99], v[168:171], v[200:203], 0
	v_mfma_f32_16x16x32_bf16 v[84:87], v[148:151], v[208:211], 0
	v_mfma_f32_16x16x32_bf16 v[80:83], v[168:171], v[208:211], 0
	v_mfma_f32_16x16x32_bf16 v[52:55], v[148:151], v[216:219], 0
	v_mfma_f32_16x16x32_bf16 v[48:51], v[168:171], v[216:219], 0
	v_mfma_f32_16x16x32_bf16 v[112:115], v[164:167], v[196:199], v[112:115]
	v_mfma_f32_16x16x32_bf16 v[116:119], v[172:175], v[196:199], v[116:119]
	v_mfma_f32_16x16x32_bf16 v[100:103], v[164:167], v[204:207], v[100:103]
	v_mfma_f32_16x16x32_bf16 v[96:99], v[172:175], v[204:207], v[96:99]
	v_mfma_f32_16x16x32_bf16 v[84:87], v[164:167], v[212:215], v[84:87]
	v_mfma_f32_16x16x32_bf16 v[80:83], v[172:175], v[212:215], v[80:83]
	v_mfma_f32_16x16x32_bf16 v[52:55], v[164:167], v[220:223], v[52:55]
	v_mfma_f32_16x16x32_bf16 v[48:51], v[172:175], v[220:223], v[48:51]
	s_setprio 0
	s_setprio 1
	v_mfma_f32_16x16x32_bf16 v[124:127], v[176:179], v[192:195], 0
	v_mfma_f32_16x16x32_bf16 v[120:123], v[184:187], v[192:195], 0
	v_mfma_f32_16x16x32_bf16 v[108:111], v[176:179], v[200:203], 0
	v_mfma_f32_16x16x32_bf16 v[104:107], v[184:187], v[200:203], 0
	v_mfma_f32_16x16x32_bf16 v[92:95], v[176:179], v[208:211], 0
	v_mfma_f32_16x16x32_bf16 v[88:91], v[184:187], v[208:211], 0
	v_mfma_f32_16x16x32_bf16 v[68:71], v[176:179], v[216:219], 0
	v_mfma_f32_16x16x32_bf16 v[64:67], v[184:187], v[216:219], 0
	v_mfma_f32_16x16x32_bf16 v[124:127], v[180:183], v[196:199], v[124:127]
	v_mfma_f32_16x16x32_bf16 v[120:123], v[188:191], v[196:199], v[120:123]
	v_mfma_f32_16x16x32_bf16 v[108:111], v[180:183], v[204:207], v[108:111]
	v_mfma_f32_16x16x32_bf16 v[104:107], v[188:191], v[204:207], v[104:107]
	v_mfma_f32_16x16x32_bf16 v[92:95], v[180:183], v[212:215], v[92:95]
	v_mfma_f32_16x16x32_bf16 v[88:91], v[188:191], v[212:215], v[88:91]
	v_mfma_f32_16x16x32_bf16 v[68:71], v[180:183], v[220:223], v[68:71]
	v_mfma_f32_16x16x32_bf16 v[64:67], v[188:191], v[220:223], v[64:67]
	s_barrier
	s_setprio 0
	s_add_i32 s88, s77, s97
	s_add_u32 s98, s46, 0x80
	s_addc_u32 s99, s47, 0
	s_mov_b32 m0, s88
	ds_read_b128 v[192:195], v161 offset:16384
	ds_read_b128 v[196:199], v161 offset:17408
	ds_read_b128 v[200:203], v161 offset:18432
	ds_read_b128 v[204:207], v161 offset:19456
	ds_read_b128 v[208:211], v161 offset:20480
	ds_read_b128 v[212:215], v161 offset:21504
	ds_read_b128 v[216:219], v161 offset:22528
	ds_read_b128 v[220:223], v161 offset:23552
	global_load_lds_dwordx4 v132, s[46:47]
	s_add_i32 m0, s88, 0x2000
	s_add_u32 s88, s46, 0x100000
	s_addc_u32 s89, s47, 0
	s_add_i32 s90, s78, s97
	global_load_lds_dwordx4 v136, s[46:47]
	s_mov_b32 m0, s90
	s_add_u32 s100, s48, 0x80
	s_addc_u32 s101, s49, 0
	global_load_lds_dwordx4 v132, s[88:89]
	s_add_i32 m0, s90, 0x2000
	s_nop 0
	global_load_lds_dwordx4 v136, s[88:89]
	s_mov_b32 m0, s94
	s_nop 0
	global_load_lds_dwordx4 v130, s[48:49]
	s_mov_b32 m0, s52
	s_nop 0
	global_load_lds_dwordx4 v134, s[48:49]
	s_waitcnt vmcnt(24)
	s_waitcnt lgkmcnt(0)
	s_setprio 1
	s_barrier
	v_mfma_f32_16x16x32_bf16 v[60:63], v[148:151], v[192:195], 0
	v_mfma_f32_16x16x32_bf16 v[56:59], v[168:171], v[192:195], 0
	v_mfma_f32_16x16x32_bf16 v[36:39], v[148:151], v[200:203], 0
	v_mfma_f32_16x16x32_bf16 v[32:35], v[168:171], v[200:203], 0
	v_mfma_f32_16x16x32_bf16 v[20:23], v[148:151], v[208:211], 0
	v_mfma_f32_16x16x32_bf16 v[16:19], v[168:171], v[208:211], 0
	v_mfma_f32_16x16x32_bf16 v[4:7], v[148:151], v[216:219], 0
	v_mfma_f32_16x16x32_bf16 v[0:3], v[168:171], v[216:219], 0
	v_mfma_f32_16x16x32_bf16 v[60:63], v[164:167], v[196:199], v[60:63]
	v_mfma_f32_16x16x32_bf16 v[56:59], v[172:175], v[196:199], v[56:59]
	v_mfma_f32_16x16x32_bf16 v[36:39], v[164:167], v[204:207], v[36:39]
	v_mfma_f32_16x16x32_bf16 v[32:35], v[172:175], v[204:207], v[32:35]
	v_mfma_f32_16x16x32_bf16 v[20:23], v[164:167], v[212:215], v[20:23]
	v_mfma_f32_16x16x32_bf16 v[16:19], v[172:175], v[212:215], v[16:19]
	v_mfma_f32_16x16x32_bf16 v[4:7], v[164:167], v[220:223], v[4:7]
	v_mfma_f32_16x16x32_bf16 v[0:3], v[172:175], v[220:223], v[0:3]
	s_setprio 0
	s_setprio 1
	v_mfma_f32_16x16x32_bf16 v[76:79], v[176:179], v[192:195], 0
	v_mfma_f32_16x16x32_bf16 v[72:75], v[184:187], v[192:195], 0
	v_mfma_f32_16x16x32_bf16 v[44:47], v[176:179], v[200:203], 0
	v_mfma_f32_16x16x32_bf16 v[40:43], v[184:187], v[200:203], 0
	v_mfma_f32_16x16x32_bf16 v[28:31], v[176:179], v[208:211], 0
	v_mfma_f32_16x16x32_bf16 v[24:27], v[184:187], v[208:211], 0
	v_mfma_f32_16x16x32_bf16 v[12:15], v[176:179], v[216:219], 0
	v_mfma_f32_16x16x32_bf16 v[8:11], v[184:187], v[216:219], 0
	v_mfma_f32_16x16x32_bf16 v[76:79], v[180:183], v[196:199], v[76:79]
	v_mfma_f32_16x16x32_bf16 v[72:75], v[188:191], v[196:199], v[72:75]
	v_mfma_f32_16x16x32_bf16 v[44:47], v[180:183], v[204:207], v[44:47]
	v_mfma_f32_16x16x32_bf16 v[40:43], v[188:191], v[204:207], v[40:43]
	v_mfma_f32_16x16x32_bf16 v[28:31], v[180:183], v[212:215], v[28:31]
	v_mfma_f32_16x16x32_bf16 v[24:27], v[188:191], v[212:215], v[24:27]
	v_mfma_f32_16x16x32_bf16 v[12:15], v[180:183], v[220:223], v[12:15]
	v_mfma_f32_16x16x32_bf16 v[8:11], v[188:191], v[220:223], v[8:11]
	s_barrier
	s_setprio 0
	s_add_i32 s88, 0, 0x18000
	v_add_u32_e32 v163, s88, v157
	s_add_i32 s89, 0, 0x1c000
	ds_read_b128 v[148:151], v163
	ds_read_b128 v[164:167], v163 offset:1024
	ds_read_b128 v[168:171], v163 offset:2048
	ds_read_b128 v[172:175], v163 offset:3072
	v_add_u32_e32 v163, s89, v157
	ds_read_b128 v[176:179], v163
	ds_read_b128 v[180:183], v163 offset:1024
	ds_read_b128 v[184:187], v163 offset:2048
	ds_read_b128 v[188:191], v163 offset:3072
	s_add_u32 s48, s48, 0x100000
	s_addc_u32 s49, s49, 0
	s_mov_b32 m0, s53
	ds_read_b128 v[192:195], v161 offset:32768
	ds_read_b128 v[196:199], v161 offset:33792
	ds_read_b128 v[200:203], v161 offset:34816
	ds_read_b128 v[204:207], v161 offset:35840
	ds_read_b128 v[208:211], v161 offset:36864
	ds_read_b128 v[212:215], v161 offset:37888
	ds_read_b128 v[216:219], v161 offset:38912
	ds_read_b128 v[220:223], v161 offset:39936
	global_load_lds_dwordx4 v130, s[48:49]
	s_mov_b32 m0, s54
	s_nop 0
	global_load_lds_dwordx4 v134, s[48:49]
	s_waitcnt vmcnt(8)
	s_waitcnt lgkmcnt(0)
	s_setprio 1
	s_barrier
	v_mfma_f32_16x16x32_bf16 v[112:115], v[148:151], v[192:195], v[112:115]
	v_mfma_f32_16x16x32_bf16 v[116:119], v[168:171], v[192:195], v[116:119]
	v_mfma_f32_16x16x32_bf16 v[100:103], v[148:151], v[200:203], v[100:103]
	v_mfma_f32_16x16x32_bf16 v[96:99], v[168:171], v[200:203], v[96:99]
	v_mfma_f32_16x16x32_bf16 v[84:87], v[148:151], v[208:211], v[84:87]
	v_mfma_f32_16x16x32_bf16 v[80:83], v[168:171], v[208:211], v[80:83]
	v_mfma_f32_16x16x32_bf16 v[52:55], v[148:151], v[216:219], v[52:55]
	v_mfma_f32_16x16x32_bf16 v[48:51], v[168:171], v[216:219], v[48:51]
	v_mfma_f32_16x16x32_bf16 v[112:115], v[164:167], v[196:199], v[112:115]
	v_mfma_f32_16x16x32_bf16 v[116:119], v[172:175], v[196:199], v[116:119]
	v_mfma_f32_16x16x32_bf16 v[100:103], v[164:167], v[204:207], v[100:103]
	v_mfma_f32_16x16x32_bf16 v[96:99], v[172:175], v[204:207], v[96:99]
	v_mfma_f32_16x16x32_bf16 v[84:87], v[164:167], v[212:215], v[84:87]
	v_mfma_f32_16x16x32_bf16 v[80:83], v[172:175], v[212:215], v[80:83]
	v_mfma_f32_16x16x32_bf16 v[52:55], v[164:167], v[220:223], v[52:55]
	v_mfma_f32_16x16x32_bf16 v[48:51], v[172:175], v[220:223], v[48:51]
	s_setprio 0
	s_setprio 1
	v_mfma_f32_16x16x32_bf16 v[124:127], v[176:179], v[192:195], v[124:127]
	v_mfma_f32_16x16x32_bf16 v[120:123], v[184:187], v[192:195], v[120:123]
	v_mfma_f32_16x16x32_bf16 v[108:111], v[176:179], v[200:203], v[108:111]
	v_mfma_f32_16x16x32_bf16 v[104:107], v[184:187], v[200:203], v[104:107]
	v_mfma_f32_16x16x32_bf16 v[92:95], v[176:179], v[208:211], v[92:95]
	v_mfma_f32_16x16x32_bf16 v[88:91], v[184:187], v[208:211], v[88:91]
	v_mfma_f32_16x16x32_bf16 v[68:71], v[176:179], v[216:219], v[68:71]
	v_mfma_f32_16x16x32_bf16 v[64:67], v[184:187], v[216:219], v[64:67]
	v_mfma_f32_16x16x32_bf16 v[124:127], v[180:183], v[196:199], v[124:127]
	v_mfma_f32_16x16x32_bf16 v[120:123], v[188:191], v[196:199], v[120:123]
	v_mfma_f32_16x16x32_bf16 v[108:111], v[180:183], v[204:207], v[108:111]
	v_mfma_f32_16x16x32_bf16 v[104:107], v[188:191], v[204:207], v[104:107]
	v_mfma_f32_16x16x32_bf16 v[92:95], v[180:183], v[212:215], v[92:95]
	v_mfma_f32_16x16x32_bf16 v[88:91], v[188:191], v[212:215], v[88:91]
	v_mfma_f32_16x16x32_bf16 v[68:71], v[180:183], v[220:223], v[68:71]
	v_mfma_f32_16x16x32_bf16 v[64:67], v[188:191], v[220:223], v[64:67]
	s_barrier
	s_setprio 0
	s_add_i32 s48, s88, s97
	s_mov_b32 m0, s48
	ds_read_b128 v[192:195], v161 offset:49152
	ds_read_b128 v[196:199], v161 offset:50176
	ds_read_b128 v[200:203], v161 offset:51200
	ds_read_b128 v[204:207], v161 offset:52224
	ds_read_b128 v[208:211], v161 offset:53248
	ds_read_b128 v[212:215], v161 offset:54272
	ds_read_b128 v[216:219], v161 offset:55296
	ds_read_b128 v[220:223], v161 offset:56320
	global_load_lds_dwordx4 v132, s[98:99]
	s_add_i32 m0, s48, 0x2000
	s_add_u32 s46, s46, 0x100080
	s_addc_u32 s47, s47, 0
	s_add_i32 s48, s89, s97
	global_load_lds_dwordx4 v136, s[98:99]
	s_mov_b32 m0, s48
	s_nop 0
	global_load_lds_dwordx4 v132, s[46:47]
	s_add_i32 m0, s48, 0x2000
	s_nop 0
	global_load_lds_dwordx4 v136, s[46:47]
	s_mov_b32 m0, s68
	s_nop 0
	global_load_lds_dwordx4 v130, s[100:101]
	s_mov_b32 m0, s69
	s_nop 0
	global_load_lds_dwordx4 v134, s[100:101]
	s_waitcnt vmcnt(8)
	s_waitcnt lgkmcnt(0)
	s_setprio 1
	s_barrier
	v_mfma_f32_16x16x32_bf16 v[60:63], v[148:151], v[192:195], v[60:63]
	v_mfma_f32_16x16x32_bf16 v[56:59], v[168:171], v[192:195], v[56:59]
	v_mfma_f32_16x16x32_bf16 v[36:39], v[148:151], v[200:203], v[36:39]
	v_mfma_f32_16x16x32_bf16 v[32:35], v[168:171], v[200:203], v[32:35]
	v_mfma_f32_16x16x32_bf16 v[20:23], v[148:151], v[208:211], v[20:23]
	v_mfma_f32_16x16x32_bf16 v[16:19], v[168:171], v[208:211], v[16:19]
	v_mfma_f32_16x16x32_bf16 v[4:7], v[148:151], v[216:219], v[4:7]
	v_mfma_f32_16x16x32_bf16 v[0:3], v[168:171], v[216:219], v[0:3]
	v_mfma_f32_16x16x32_bf16 v[60:63], v[164:167], v[196:199], v[60:63]
	v_mfma_f32_16x16x32_bf16 v[56:59], v[172:175], v[196:199], v[56:59]
	v_mfma_f32_16x16x32_bf16 v[36:39], v[164:167], v[204:207], v[36:39]
	v_mfma_f32_16x16x32_bf16 v[32:35], v[172:175], v[204:207], v[32:35]
	v_mfma_f32_16x16x32_bf16 v[20:23], v[164:167], v[212:215], v[20:23]
	v_mfma_f32_16x16x32_bf16 v[16:19], v[172:175], v[212:215], v[16:19]
	v_mfma_f32_16x16x32_bf16 v[4:7], v[164:167], v[220:223], v[4:7]
	v_mfma_f32_16x16x32_bf16 v[0:3], v[172:175], v[220:223], v[0:3]
	s_setprio 0
	s_setprio 1
	v_mfma_f32_16x16x32_bf16 v[76:79], v[176:179], v[192:195], v[76:79]
	v_mfma_f32_16x16x32_bf16 v[72:75], v[184:187], v[192:195], v[72:75]
	v_mfma_f32_16x16x32_bf16 v[44:47], v[176:179], v[200:203], v[44:47]
	v_mfma_f32_16x16x32_bf16 v[40:43], v[184:187], v[200:203], v[40:43]
	v_mfma_f32_16x16x32_bf16 v[28:31], v[176:179], v[208:211], v[28:31]
	v_mfma_f32_16x16x32_bf16 v[24:27], v[184:187], v[208:211], v[24:27]
	v_mfma_f32_16x16x32_bf16 v[12:15], v[176:179], v[216:219], v[12:15]
	v_mfma_f32_16x16x32_bf16 v[8:11], v[184:187], v[216:219], v[8:11]
	v_mfma_f32_16x16x32_bf16 v[76:79], v[180:183], v[196:199], v[76:79]
	v_mfma_f32_16x16x32_bf16 v[72:75], v[188:191], v[196:199], v[72:75]
	v_mfma_f32_16x16x32_bf16 v[44:47], v[180:183], v[204:207], v[44:47]
	v_mfma_f32_16x16x32_bf16 v[40:43], v[188:191], v[204:207], v[40:43]
	v_mfma_f32_16x16x32_bf16 v[28:31], v[180:183], v[212:215], v[28:31]
	v_mfma_f32_16x16x32_bf16 v[24:27], v[188:191], v[212:215], v[24:27]
	v_mfma_f32_16x16x32_bf16 v[12:15], v[180:183], v[220:223], v[12:15]
	v_mfma_f32_16x16x32_bf16 v[8:11], v[188:191], v[220:223], v[8:11]
	s_barrier
	s_setprio 0
	s_add_u32 s85, s85, 0x100
	s_addc_u32 s86, s86, 0
	s_add_u32 s44, s44, 0x100
	s_addc_u32 s45, s45, 0
	s_cmp_ge_u32 s87, s84
	s_mov_b32 s46, s87
	s_cbranch_scc1 .Lpeel_done_3

.LBB0_2437:
	s_mov_b64 s[12:13], 0x80
	v_lshl_add_u64 v[6:7], v[6:7], 0, s[12:13]
	s_add_i32 m0, s94, 0x18000
	s_waitcnt vmcnt(2)
	s_barrier
	global_load_lds_dwordx4 v[6:7], off
	v_lshl_add_u64 v[4:5], v[4:5], 0, s[12:13]
	s_add_i32 m0, s94, 0x1a000
	s_add_i32 s54, s94, 0x8000
	s_add_i32 s55, s94, 0xa000
	global_load_lds_dwordx4 v[4:5], off
	v_lshl_add_u64 v[0:1], v[0:1], 0, s[12:13]
	s_mov_b32 m0, s54
	s_add_u32 s0, s44, 0x400080
	global_load_lds_dwordx4 v[0:1], off
	v_lshl_add_u64 v[0:1], v[2:3], 0, s[12:13]
	s_mov_b32 m0, s55
	s_addc_u32 s1, s45, 0
	global_load_lds_dwordx4 v[0:1], off
	v_lshl_add_u64 v[0:1], s[0:1], 0, v[194:195]
	s_add_i32 m0, s94, 0x1c000
	v_or_b32_e32 v225, s92, v222
	global_load_lds_dwordx4 v[0:1], off
	v_lshl_add_u64 v[0:1], s[0:1], 0, v[198:199]
	s_add_i32 m0, s94, 0x1e000
	v_and_b32_e32 v2, 48, v224
	global_load_lds_dwordx4 v[0:1], off
	v_lshlrev_b32_e32 v1, 6, v225
	s_movk_i32 s0, 0x3c0
	v_ashrrev_i32_e32 v0, 6, v224
	v_and_or_b32 v1, v1, s0, v2
	v_readlane_b32 s0, v254, 39
	v_lshlrev_b32_e32 v4, 2, v225
	v_and_b32_e32 v4, 32, v4
	v_lshl_add_u32 v3, v0, 10, s0
	v_bitop3_b32 v3, v1, v3, v4 bitop3:0xde
	v_lshl_or_b32 v1, v222, 6, v2
	v_readlane_b32 s0, v255, 11
	v_lshlrev_b32_e32 v2, 2, v222
	v_and_b32_e32 v2, 32, v2
	v_add_lshl_u32 v0, v0, s0, 10
	v_bitop3_b32 v226, v1, v0, v2 bitop3:0xde
	v_add_u32_e32 v0, s97, v224
	v_readlane_b32 s4, v254, 63
	v_ashrrev_i32_e32 v1, 31, v0
	v_readlane_b32 s5, v255, 0
	s_waitcnt vmcnt(0)
	s_add_i32 s68, 0, 0x10000
	s_add_i32 s69, 0, 0x14000
	v_lshl_add_u64 v[200:201], v[0:1], 4, s[4:5]
	v_cndmask_b32_e64 v0, 0, -1, s[8:9]
	v_readlane_b32 s4, v254, 57
	v_readfirstlane_b32 s63, v0
	v_lshlrev_b32_e32 v0, 18, v8
	v_and_b32_e32 v0, 0xfff80000, v0
	s_lshr_b32 s4, s4, 29
	v_lshl_add_u32 v0, v9, 15, v0
	v_and_b32_e32 v1, 1, v8
	s_add_i32 s4, s91, s4
	v_lshl_or_b32 v0, v1, 6, v0
	s_ashr_i32 s64, s4, 3
	s_and_b32 s4, s4, 0x7fffff8
	v_lshl_add_u32 v202, v10, 1, v0
	v_lshlrev_b32_e32 v0, 18, v11
	s_sub_i32 s4, s91, s4
	v_and_b32_e32 v0, 0xfff80000, v0
	s_lshl_b32 s4, s4, 5
	v_lshl_add_u32 v0, v12, 15, v0
	v_and_b32_e32 v1, 1, v11
	s_ashr_i32 s5, s4, 31
	v_lshl_or_b32 v0, v1, 6, v0
	v_add_u32_e32 v227, s95, v223
	v_cmp_eq_u32_e64 s[0:1], 0, v224
	s_addk_i32 s64, 0x200
	s_lshl_b64 s[14:15], s[4:5], 7
	v_mov_b32_e32 v203, v195
	v_lshl_add_u32 v204, v13, 1, v0
	v_mov_b32_e32 v205, v195
	v_add_u32_e32 v228, s68, v226
	v_add_u32_e32 v229, s69, v226
	v_add_u32_e32 v230, 0, v3
	s_mov_b64 s[16:17], 0x2c00
	s_mov_b64 s[18:19], 0x3000
	s_mov_b64 s[20:21], 0x3400
	s_mov_b64 s[22:23], 0x3800
	s_mov_b64 s[24:25], 0x3c00
	v_mov_b64_e32 v[206:207], 0x220
	s_mov_b32 s35, s11
	s_barrier
	s_branch .LBB0_2440

.LBB0_2452:
	s_cmp_lt_u32 s35, 0x3fffffff
	s_cselect_b64 s[38:39], -1, 0
	s_ashr_i32 s35, s34, 31
	s_and_b64 s[38:39], s[4:5], s[38:39]
	s_lshl_b64 s[4:5], s[34:35], 23
	s_add_u32 s4, s2, s4
	s_addc_u32 s5, s3, s5
	s_add_u32 s4, s4, s36
	s_addc_u32 s5, s5, s37
	s_and_b64 s[48:49], s[38:39], exec
	s_cselect_b32 s35, s5, s47
	s_cselect_b32 s41, s4, s46
	s_ashr_i32 s31, s30, 31
	s_lshl_b64 s[48:49], s[30:31], 23
	v_readlane_b32 s78, v254, 54
	v_readlane_b32 s79, v254, 55
	s_add_u32 s31, s78, s48
	s_addc_u32 s43, s79, s49
	s_add_u32 s36, s31, s36
	s_addc_u32 s37, s43, s37
	s_and_b64 s[48:49], s[38:39], exec
	s_cselect_b32 s31, s37, s45
	s_cselect_b32 s43, s36, s44
	s_add_i32 s75, s76, -2
	s_add_u32 s77, s44, 0x100
	s_addc_u32 s78, s45, 0
	s_add_u32 s44, s46, 0x400080
	s_addc_u32 s45, s47, 0
	s_mov_b32 s46, 0
	ds_read_b128 v[128:131], v228
	ds_read_b128 v[132:135], v228 offset:1024
	ds_read_b128 v[136:139], v228 offset:2048
	ds_read_b128 v[140:143], v228 offset:3072
	ds_read_b128 v[144:147], v229
	ds_read_b128 v[148:151], v229 offset:1024
	ds_read_b128 v[152:155], v229 offset:2048
	ds_read_b128 v[156:159], v229 offset:3072
	s_add_i32 s79, s46, 2
	s_add_u32 s47, s44, 0xffc00080
	s_addc_u32 s48, s45, -1
	s_cmp_eq_u32 s75, s46
	s_cselect_b32 s46, s43, s77
	s_cselect_b32 s49, s35, s48
	s_cselect_b32 s48, s41, s47
	s_cselect_b32 s47, s31, s78
	s_add_i32 m0, s94, 0xc000
	ds_read_b128 v[160:163], v230
	ds_read_b128 v[164:167], v230 offset:1024
	ds_read_b128 v[168:171], v230 offset:2048
	ds_read_b128 v[172:175], v230 offset:3072
	ds_read_b128 v[176:179], v230 offset:4096
	ds_read_b128 v[180:183], v230 offset:5120
	ds_read_b128 v[184:187], v230 offset:6144
	ds_read_b128 v[188:191], v230 offset:7168
	global_load_lds_dwordx4 v202, s[44:45]
	s_add_i32 m0, s94, 0xe000
	s_nop 0
	global_load_lds_dwordx4 v204, s[44:45]
	s_waitcnt vmcnt(24)
	s_waitcnt lgkmcnt(0)
	s_setprio 1
	s_barrier
	v_mfma_f32_16x16x32_bf16 v[112:115], v[128:131], v[160:163], 0
	v_mfma_f32_16x16x32_bf16 v[116:119], v[136:139], v[160:163], 0
	v_mfma_f32_16x16x32_bf16 v[100:103], v[128:131], v[168:171], 0
	v_mfma_f32_16x16x32_bf16 v[96:99], v[136:139], v[168:171], 0
	v_mfma_f32_16x16x32_bf16 v[84:87], v[128:131], v[176:179], 0
	v_mfma_f32_16x16x32_bf16 v[80:83], v[136:139], v[176:179], 0
	v_mfma_f32_16x16x32_bf16 v[52:55], v[128:131], v[184:187], 0
	v_mfma_f32_16x16x32_bf16 v[48:51], v[136:139], v[184:187], 0
	v_mfma_f32_16x16x32_bf16 v[112:115], v[132:135], v[164:167], v[112:115]
	v_mfma_f32_16x16x32_bf16 v[116:119], v[140:143], v[164:167], v[116:119]
	v_mfma_f32_16x16x32_bf16 v[100:103], v[132:135], v[172:175], v[100:103]
	v_mfma_f32_16x16x32_bf16 v[96:99], v[140:143], v[172:175], v[96:99]
	v_mfma_f32_16x16x32_bf16 v[84:87], v[132:135], v[180:183], v[84:87]
	v_mfma_f32_16x16x32_bf16 v[80:83], v[140:143], v[180:183], v[80:83]
	v_mfma_f32_16x16x32_bf16 v[52:55], v[132:135], v[188:191], v[52:55]
	v_mfma_f32_16x16x32_bf16 v[48:51], v[140:143], v[188:191], v[48:51]
	s_setprio 0
	s_setprio 1
	v_mfma_f32_16x16x32_bf16 v[124:127], v[144:147], v[160:163], 0
	v_mfma_f32_16x16x32_bf16 v[120:123], v[152:155], v[160:163], 0
	v_mfma_f32_16x16x32_bf16 v[108:111], v[144:147], v[168:171], 0
	v_mfma_f32_16x16x32_bf16 v[104:107], v[152:155], v[168:171], 0
	v_mfma_f32_16x16x32_bf16 v[92:95], v[144:147], v[176:179], 0
	v_mfma_f32_16x16x32_bf16 v[88:91], v[152:155], v[176:179], 0
	v_mfma_f32_16x16x32_bf16 v[68:71], v[144:147], v[184:187], 0
	v_mfma_f32_16x16x32_bf16 v[64:67], v[152:155], v[184:187], 0
	v_mfma_f32_16x16x32_bf16 v[124:127], v[148:151], v[164:167], v[124:127]
	v_mfma_f32_16x16x32_bf16 v[120:123], v[156:159], v[164:167], v[120:123]
	v_mfma_f32_16x16x32_bf16 v[108:111], v[148:151], v[172:175], v[108:111]
	v_mfma_f32_16x16x32_bf16 v[104:107], v[156:159], v[172:175], v[104:107]
	v_mfma_f32_16x16x32_bf16 v[92:95], v[148:151], v[180:183], v[92:95]
	v_mfma_f32_16x16x32_bf16 v[88:91], v[156:159], v[180:183], v[88:91]
	v_mfma_f32_16x16x32_bf16 v[68:71], v[148:151], v[188:191], v[68:71]
	v_mfma_f32_16x16x32_bf16 v[64:67], v[156:159], v[188:191], v[64:67]
	s_barrier
	s_setprio 0
	s_add_i32 s80, s68, s97
	s_add_u32 s98, s46, 0x80
	s_addc_u32 s99, s47, 0
	s_mov_b32 m0, s80
	ds_read_b128 v[160:163], v230 offset:16384
	ds_read_b128 v[164:167], v230 offset:17408
	ds_read_b128 v[168:171], v230 offset:18432
	ds_read_b128 v[172:175], v230 offset:19456
	ds_read_b128 v[176:179], v230 offset:20480
	ds_read_b128 v[180:183], v230 offset:21504
	ds_read_b128 v[184:187], v230 offset:22528
	ds_read_b128 v[188:191], v230 offset:23552
	global_load_lds_dwordx4 v194, s[46:47]
	s_add_i32 m0, s80, 0x2000
	s_add_u32 s80, s46, 0x400000
	s_addc_u32 s81, s47, 0
	s_add_i32 s84, s69, s97
	global_load_lds_dwordx4 v198, s[46:47]
	s_mov_b32 m0, s84
	s_add_u32 s100, s48, 0x80
	s_addc_u32 s101, s49, 0
	global_load_lds_dwordx4 v194, s[80:81]
	s_add_i32 m0, s84, 0x2000
	s_nop 0
	global_load_lds_dwordx4 v198, s[80:81]
	s_mov_b32 m0, s94
	s_nop 0
	global_load_lds_dwordx4 v192, s[48:49]
	s_mov_b32 m0, s51
	s_nop 0
	global_load_lds_dwordx4 v196, s[48:49]
	s_waitcnt vmcnt(24)
	s_waitcnt lgkmcnt(0)
	s_setprio 1
	s_barrier
	v_mfma_f32_16x16x32_bf16 v[60:63], v[128:131], v[160:163], 0
	v_mfma_f32_16x16x32_bf16 v[56:59], v[136:139], v[160:163], 0
	v_mfma_f32_16x16x32_bf16 v[36:39], v[128:131], v[168:171], 0
	v_mfma_f32_16x16x32_bf16 v[32:35], v[136:139], v[168:171], 0
	v_mfma_f32_16x16x32_bf16 v[20:23], v[128:131], v[176:179], 0
	v_mfma_f32_16x16x32_bf16 v[16:19], v[136:139], v[176:179], 0
	v_mfma_f32_16x16x32_bf16 v[4:7], v[128:131], v[184:187], 0
	v_mfma_f32_16x16x32_bf16 v[0:3], v[136:139], v[184:187], 0
	v_mfma_f32_16x16x32_bf16 v[60:63], v[132:135], v[164:167], v[60:63]
	v_mfma_f32_16x16x32_bf16 v[56:59], v[140:143], v[164:167], v[56:59]
	v_mfma_f32_16x16x32_bf16 v[36:39], v[132:135], v[172:175], v[36:39]
	v_mfma_f32_16x16x32_bf16 v[32:35], v[140:143], v[172:175], v[32:35]
	v_mfma_f32_16x16x32_bf16 v[20:23], v[132:135], v[180:183], v[20:23]
	v_mfma_f32_16x16x32_bf16 v[16:19], v[140:143], v[180:183], v[16:19]
	v_mfma_f32_16x16x32_bf16 v[4:7], v[132:135], v[188:191], v[4:7]
	v_mfma_f32_16x16x32_bf16 v[0:3], v[140:143], v[188:191], v[0:3]
	s_setprio 0
	s_setprio 1
	v_mfma_f32_16x16x32_bf16 v[76:79], v[144:147], v[160:163], 0
	v_mfma_f32_16x16x32_bf16 v[72:75], v[152:155], v[160:163], 0
	v_mfma_f32_16x16x32_bf16 v[44:47], v[144:147], v[168:171], 0
	v_mfma_f32_16x16x32_bf16 v[40:43], v[152:155], v[168:171], 0
	v_mfma_f32_16x16x32_bf16 v[28:31], v[144:147], v[176:179], 0
	v_mfma_f32_16x16x32_bf16 v[24:27], v[152:155], v[176:179], 0
	v_mfma_f32_16x16x32_bf16 v[12:15], v[144:147], v[184:187], 0
	v_mfma_f32_16x16x32_bf16 v[8:11], v[152:155], v[184:187], 0
	v_mfma_f32_16x16x32_bf16 v[76:79], v[148:151], v[164:167], v[76:79]
	v_mfma_f32_16x16x32_bf16 v[72:75], v[156:159], v[164:167], v[72:75]
	v_mfma_f32_16x16x32_bf16 v[44:47], v[148:151], v[172:175], v[44:47]
	v_mfma_f32_16x16x32_bf16 v[40:43], v[156:159], v[172:175], v[40:43]
	v_mfma_f32_16x16x32_bf16 v[28:31], v[148:151], v[180:183], v[28:31]
	v_mfma_f32_16x16x32_bf16 v[24:27], v[156:159], v[180:183], v[24:27]
	v_mfma_f32_16x16x32_bf16 v[12:15], v[148:151], v[188:191], v[12:15]
	v_mfma_f32_16x16x32_bf16 v[8:11], v[156:159], v[188:191], v[8:11]
	s_barrier
	s_setprio 0
	s_add_i32 s80, 0, 0x18000
	s_add_i32 s81, 0, 0x1c000
	v_add_u32_e32 v140, s80, v226
	v_add_u32_e32 v156, s81, v226
	ds_read_b128 v[128:131], v140
	ds_read_b128 v[132:135], v140 offset:1024
	ds_read_b128 v[136:139], v140 offset:2048
	ds_read_b128 v[140:143], v140 offset:3072
	ds_read_b128 v[144:147], v156
	ds_read_b128 v[148:151], v156 offset:1024
	ds_read_b128 v[152:155], v156 offset:2048
	ds_read_b128 v[156:159], v156 offset:3072
	s_add_u32 s48, s48, 0x400000
	s_addc_u32 s49, s49, 0
	s_mov_b32 m0, s52
	ds_read_b128 v[160:163], v230 offset:32768
	ds_read_b128 v[164:167], v230 offset:33792
	ds_read_b128 v[168:171], v230 offset:34816
	ds_read_b128 v[172:175], v230 offset:35840
	ds_read_b128 v[176:179], v230 offset:36864
	ds_read_b128 v[180:183], v230 offset:37888
	ds_read_b128 v[184:187], v230 offset:38912
	ds_read_b128 v[188:191], v230 offset:39936
	global_load_lds_dwordx4 v192, s[48:49]
	s_mov_b32 m0, s53
	s_nop 0
	global_load_lds_dwordx4 v196, s[48:49]
	s_waitcnt vmcnt(8)
	s_waitcnt lgkmcnt(0)
	s_setprio 1
	s_barrier
	v_mfma_f32_16x16x32_bf16 v[112:115], v[128:131], v[160:163], v[112:115]
	v_mfma_f32_16x16x32_bf16 v[116:119], v[136:139], v[160:163], v[116:119]
	v_mfma_f32_16x16x32_bf16 v[100:103], v[128:131], v[168:171], v[100:103]
	v_mfma_f32_16x16x32_bf16 v[96:99], v[136:139], v[168:171], v[96:99]
	v_mfma_f32_16x16x32_bf16 v[84:87], v[128:131], v[176:179], v[84:87]
	v_mfma_f32_16x16x32_bf16 v[80:83], v[136:139], v[176:179], v[80:83]
	v_mfma_f32_16x16x32_bf16 v[52:55], v[128:131], v[184:187], v[52:55]
	v_mfma_f32_16x16x32_bf16 v[48:51], v[136:139], v[184:187], v[48:51]
	v_mfma_f32_16x16x32_bf16 v[112:115], v[132:135], v[164:167], v[112:115]
	v_mfma_f32_16x16x32_bf16 v[116:119], v[140:143], v[164:167], v[116:119]
	v_mfma_f32_16x16x32_bf16 v[100:103], v[132:135], v[172:175], v[100:103]
	v_mfma_f32_16x16x32_bf16 v[96:99], v[140:143], v[172:175], v[96:99]
	v_mfma_f32_16x16x32_bf16 v[84:87], v[132:135], v[180:183], v[84:87]
	v_mfma_f32_16x16x32_bf16 v[80:83], v[140:143], v[180:183], v[80:83]
	v_mfma_f32_16x16x32_bf16 v[52:55], v[132:135], v[188:191], v[52:55]
	v_mfma_f32_16x16x32_bf16 v[48:51], v[140:143], v[188:191], v[48:51]
	s_setprio 0
	s_setprio 1
	v_mfma_f32_16x16x32_bf16 v[124:127], v[144:147], v[160:163], v[124:127]
	v_mfma_f32_16x16x32_bf16 v[120:123], v[152:155], v[160:163], v[120:123]
	v_mfma_f32_16x16x32_bf16 v[108:111], v[144:147], v[168:171], v[108:111]
	v_mfma_f32_16x16x32_bf16 v[104:107], v[152:155], v[168:171], v[104:107]
	v_mfma_f32_16x16x32_bf16 v[92:95], v[144:147], v[176:179], v[92:95]
	v_mfma_f32_16x16x32_bf16 v[88:91], v[152:155], v[176:179], v[88:91]
	v_mfma_f32_16x16x32_bf16 v[68:71], v[144:147], v[184:187], v[68:71]
	v_mfma_f32_16x16x32_bf16 v[64:67], v[152:155], v[184:187], v[64:67]
	v_mfma_f32_16x16x32_bf16 v[124:127], v[148:151], v[164:167], v[124:127]
	v_mfma_f32_16x16x32_bf16 v[120:123], v[156:159], v[164:167], v[120:123]
	v_mfma_f32_16x16x32_bf16 v[108:111], v[148:151], v[172:175], v[108:111]
	v_mfma_f32_16x16x32_bf16 v[104:107], v[156:159], v[172:175], v[104:107]
	v_mfma_f32_16x16x32_bf16 v[92:95], v[148:151], v[180:183], v[92:95]
	v_mfma_f32_16x16x32_bf16 v[88:91], v[156:159], v[180:183], v[88:91]
	v_mfma_f32_16x16x32_bf16 v[68:71], v[148:151], v[188:191], v[68:71]
	v_mfma_f32_16x16x32_bf16 v[64:67], v[156:159], v[188:191], v[64:67]
	s_barrier
	s_setprio 0
	s_add_i32 s48, s80, s97
	s_mov_b32 m0, s48
	ds_read_b128 v[160:163], v230 offset:49152
	ds_read_b128 v[164:167], v230 offset:50176
	ds_read_b128 v[168:171], v230 offset:51200
	ds_read_b128 v[172:175], v230 offset:52224
	ds_read_b128 v[176:179], v230 offset:53248
	ds_read_b128 v[180:183], v230 offset:54272
	ds_read_b128 v[184:187], v230 offset:55296
	ds_read_b128 v[188:191], v230 offset:56320
	global_load_lds_dwordx4 v194, s[98:99]
	s_add_i32 m0, s48, 0x2000
	s_add_u32 s46, s46, 0x400080
	s_addc_u32 s47, s47, 0
	s_add_i32 s48, s81, s97
	global_load_lds_dwordx4 v198, s[98:99]
	s_mov_b32 m0, s48
	s_nop 0
	global_load_lds_dwordx4 v194, s[46:47]
	s_add_i32 m0, s48, 0x2000
	s_nop 0
	global_load_lds_dwordx4 v198, s[46:47]
	s_mov_b32 m0, s54
	s_nop 0
	global_load_lds_dwordx4 v192, s[100:101]
	s_mov_b32 m0, s55
	s_nop 0
	global_load_lds_dwordx4 v196, s[100:101]
	s_waitcnt vmcnt(8)
	s_waitcnt lgkmcnt(0)
	s_setprio 1
	s_barrier
	v_mfma_f32_16x16x32_bf16 v[60:63], v[128:131], v[160:163], v[60:63]
	v_mfma_f32_16x16x32_bf16 v[56:59], v[136:139], v[160:163], v[56:59]
	v_mfma_f32_16x16x32_bf16 v[36:39], v[128:131], v[168:171], v[36:39]
	v_mfma_f32_16x16x32_bf16 v[32:35], v[136:139], v[168:171], v[32:35]
	v_mfma_f32_16x16x32_bf16 v[20:23], v[128:131], v[176:179], v[20:23]
	v_mfma_f32_16x16x32_bf16 v[16:19], v[136:139], v[176:179], v[16:19]
	v_mfma_f32_16x16x32_bf16 v[4:7], v[128:131], v[184:187], v[4:7]
	v_mfma_f32_16x16x32_bf16 v[0:3], v[136:139], v[184:187], v[0:3]
	v_mfma_f32_16x16x32_bf16 v[60:63], v[132:135], v[164:167], v[60:63]
	v_mfma_f32_16x16x32_bf16 v[56:59], v[140:143], v[164:167], v[56:59]
	v_mfma_f32_16x16x32_bf16 v[36:39], v[132:135], v[172:175], v[36:39]
	v_mfma_f32_16x16x32_bf16 v[32:35], v[140:143], v[172:175], v[32:35]
	v_mfma_f32_16x16x32_bf16 v[20:23], v[132:135], v[180:183], v[20:23]
	v_mfma_f32_16x16x32_bf16 v[16:19], v[140:143], v[180:183], v[16:19]
	v_mfma_f32_16x16x32_bf16 v[4:7], v[132:135], v[188:191], v[4:7]
	v_mfma_f32_16x16x32_bf16 v[0:3], v[140:143], v[188:191], v[0:3]
	s_setprio 0
	s_setprio 1
	v_mfma_f32_16x16x32_bf16 v[76:79], v[144:147], v[160:163], v[76:79]
	v_mfma_f32_16x16x32_bf16 v[72:75], v[152:155], v[160:163], v[72:75]
	v_mfma_f32_16x16x32_bf16 v[44:47], v[144:147], v[168:171], v[44:47]
	v_mfma_f32_16x16x32_bf16 v[40:43], v[152:155], v[168:171], v[40:43]
	v_mfma_f32_16x16x32_bf16 v[28:31], v[144:147], v[176:179], v[28:31]
	v_mfma_f32_16x16x32_bf16 v[24:27], v[152:155], v[176:179], v[24:27]
	v_mfma_f32_16x16x32_bf16 v[12:15], v[144:147], v[184:187], v[12:15]
	v_mfma_f32_16x16x32_bf16 v[8:11], v[152:155], v[184:187], v[8:11]
	v_mfma_f32_16x16x32_bf16 v[76:79], v[148:151], v[164:167], v[76:79]
	v_mfma_f32_16x16x32_bf16 v[72:75], v[156:159], v[164:167], v[72:75]
	v_mfma_f32_16x16x32_bf16 v[44:47], v[148:151], v[172:175], v[44:47]
	v_mfma_f32_16x16x32_bf16 v[40:43], v[156:159], v[172:175], v[40:43]
	v_mfma_f32_16x16x32_bf16 v[28:31], v[148:151], v[180:183], v[28:31]
	v_mfma_f32_16x16x32_bf16 v[24:27], v[156:159], v[180:183], v[24:27]
	v_mfma_f32_16x16x32_bf16 v[12:15], v[148:151], v[188:191], v[12:15]
	v_mfma_f32_16x16x32_bf16 v[8:11], v[156:159], v[188:191], v[8:11]
	s_barrier
	s_setprio 0
	s_add_u32 s77, s77, 0x100
	s_addc_u32 s78, s78, 0
	s_add_u32 s44, s44, 0x100
	s_addc_u32 s45, s45, 0
	s_cmp_ge_u32 s79, s76
	s_mov_b32 s46, s79
	s_cbranch_scc1 .Lpeel_done_4
